# baseline (speedup 1.0000x reference)
; DEVI void rwkv_scan_item(int TID_, int BID_, PREF p, int g, int item, char* shm) {
;     ...
;     const int buf = tb & 1;
;     if (wave >= 4) {
;       if (tb + 1 < nblk) commit_block(buf ^ 1);
;       if (tb + 2 < nblk) issue_block(tb + 2);
;       if (tb > 0) flush_block(tb - 1, buf ^ 1);
;     } else {
;       const float* ob = opbuf + ((size_t)buf * TB * 16 + jg) * 20;
;       const float* vb = vbuf + buf * TB * 16 + row;
;       float* yb = ybuf + ((size_t)buf * TB * 16 + row) * 8 + (jg >> 1);
;       OpsR n1 = ld(ob, vb, 0), n2 = ld(ob, vb, 1);
; #pragma unroll
;       for (int s = 0; s < TB; ++s) {
;         OpsR c = n1;
;         n1 = n2;
;         if (s + 2 < TB) n2 = ld(ob, vb, s + 2);
;         f2v a01 = {c.a.x, c.a.y}, a23 = {c.a.z, c.a.w}, w01 = {c.w.x, c.w.y}, w23 = {c.w.z, c.w.w},
;             b01 = {c.b.x, c.b.y}, b23 = {c.b.z, c.b.w}, k01 = {c.k.x, c.k.y}, k23 = {c.k.z, c.k.w},
;             r01 = {c.r.x, c.r.y}, r23 = {c.r.z, c.r.w};
;         f2v vv = {c.v, c.v};
;         f2v vk01 = vv * k01, vk23 = vv * k23;
;         f2v t = S01 * a01;
;         t = S23 * a23 + t;
;         float sa = allreduce16(t.x + t.y);
;         f2v sv = {sa, sa};
;         S01 = S01 * w01 + (sv * b01 + vk01);
;         S23 = S23 * w23 + (sv * b23 + vk23);
;         f2v u = S01 * r01;
;         u = S23 * r23 + u;
;         float uu = u.x + u.y;
;         uu += dppmov<0xB1>(uu);
;         yb[s * 128] = uu;
;       }
.LBB0_210:
	v_and_b32_e32 v44, 1, v43
	s_and_saveexec_b64 s[24:25], s[8:9]
	s_xor_b64 s[24:25], exec, s[24:25]
	s_cbranch_execz .LBB0_212
	v_lshlrev_b32_e32 v186, 9, v44
	v_or_b32_e32 v237, v186, v2
	v_mul_u32_u24_e32 v237, 0x50, v237
	v_lshl_add_u32 v238, v44, 11, v40
	v_add_u32_e32 v193, v186, v39
	v_lshl_add_u32 v193, v193, 5, v41
	ds_read_b128 v[136:139], v237
	ds_read_b128 v[140:143], v237 offset:16
	ds_read_b128 v[144:147], v237 offset:32
	ds_read_b128 v[148:151], v237 offset:48
	ds_read_b128 v[152:155], v237 offset:64
	ds_read_b32 v156, v238
	ds_read_b128 v[160:163], v237 offset:1280
	ds_read_b128 v[164:167], v237 offset:1296
	ds_read_b128 v[168:171], v237 offset:1312
	ds_read_b128 v[172:175], v237 offset:1328
	ds_read_b128 v[176:179], v237 offset:1344
	ds_read_b32 v180, v238 offset:64
	s_waitcnt lgkmcnt(6)
	v_pk_mul_f32 v[186:187], v[32:33], v[136:137]
	v_pk_fma_f32 v[186:187], v[34:35], v[138:139], v[186:187]
	ds_read_b128 v[216:219], v237 offset:2560
	ds_read_b128 v[220:223], v237 offset:2576
	ds_read_b128 v[224:227], v237 offset:2592
	ds_read_b128 v[228:231], v237 offset:2608
	ds_read_b128 v[232:235], v237 offset:2624
	ds_read_b32 v184, v238 offset:128
	v_add_f32_e32 v188, v186, v187
	v_pk_mul_f32 v[158:159], v[148:149], v[156:157] op_sel_hi:[1,0]
	s_nop 0
	v_add_f32_dpp v188, v188, v188 quad_perm:[1,0,3,2] row_mask:0xf bank_mask:0xf bound_ctrl:1
	v_pk_mul_f32 v[182:183], v[150:151], v[156:157] op_sel_hi:[1,0]
	s_nop 0
	v_add_f32_dpp v188, v188, v188 quad_perm:[2,3,0,1] row_mask:0xf bank_mask:0xf bound_ctrl:1
	v_pk_fma_f32 v[194:195], v[32:33], v[140:141], v[158:159]
	s_nop 0
	v_add_f32_dpp v188, v188, v188 row_half_mirror row_mask:0xf bank_mask:0xf bound_ctrl:1
	v_pk_fma_f32 v[214:215], v[34:35], v[142:143], v[182:183]
	s_nop 0
	v_add_f32_dpp v188, v188, v188 row_mirror row_mask:0xf bank_mask:0xf bound_ctrl:1
	v_pk_fma_f32 v[32:33], v[144:145], v[188:189], v[194:195] op_sel_hi:[1,0,1]
	v_pk_fma_f32 v[34:35], v[146:147], v[188:189], v[214:215] op_sel_hi:[1,0,1]
	s_waitcnt lgkmcnt(6)
	v_pk_mul_f32 v[186:187], v[32:33], v[160:161]
	v_pk_mul_f32 v[190:191], v[32:33], v[152:153]
	v_pk_fma_f32 v[186:187], v[34:35], v[162:163], v[186:187]
	v_pk_fma_f32 v[190:191], v[34:35], v[154:155], v[190:191]
	ds_read_b128 v[136:139], v237 offset:3840
	ds_read_b128 v[140:143], v237 offset:3856
	ds_read_b128 v[144:147], v237 offset:3872
	ds_read_b128 v[148:151], v237 offset:3888
	ds_read_b128 v[152:155], v237 offset:3904
	ds_read_b32 v156, v238 offset:192
	v_add_f32_e32 v188, v186, v187
	v_pk_mul_f32 v[158:159], v[172:173], v[180:181] op_sel_hi:[1,0]
	v_add_f32_e32 v192, v190, v191
	v_add_f32_dpp v188, v188, v188 quad_perm:[1,0,3,2] row_mask:0xf bank_mask:0xf bound_ctrl:1
	v_pk_mul_f32 v[182:183], v[174:175], v[180:181] op_sel_hi:[1,0]
	v_add_f32_dpp v192, v192, v192 quad_perm:[1,0,3,2] row_mask:0xf bank_mask:0xf bound_ctrl:1
	v_add_f32_dpp v188, v188, v188 quad_perm:[2,3,0,1] row_mask:0xf bank_mask:0xf bound_ctrl:1
	v_pk_fma_f32 v[194:195], v[32:33], v[164:165], v[158:159]
	ds_write_b32 v193, v192
	v_add_f32_dpp v188, v188, v188 row_half_mirror row_mask:0xf bank_mask:0xf bound_ctrl:1
	v_pk_fma_f32 v[214:215], v[34:35], v[166:167], v[182:183]
	s_nop 0
	v_add_f32_dpp v188, v188, v188 row_mirror row_mask:0xf bank_mask:0xf bound_ctrl:1
	v_pk_fma_f32 v[32:33], v[168:169], v[188:189], v[194:195] op_sel_hi:[1,0,1]
	v_pk_fma_f32 v[34:35], v[170:171], v[188:189], v[214:215] op_sel_hi:[1,0,1]
	s_waitcnt lgkmcnt(7)
	v_pk_mul_f32 v[186:187], v[32:33], v[216:217]
	v_pk_mul_f32 v[190:191], v[32:33], v[176:177]
	v_pk_fma_f32 v[186:187], v[34:35], v[218:219], v[186:187]
	v_pk_fma_f32 v[190:191], v[34:35], v[178:179], v[190:191]
	ds_read_b128 v[160:163], v237 offset:5120
	ds_read_b128 v[164:167], v237 offset:5136
	ds_read_b128 v[168:171], v237 offset:5152
	ds_read_b128 v[172:175], v237 offset:5168
	ds_read_b128 v[176:179], v237 offset:5184
	ds_read_b32 v180, v238 offset:256
	v_add_f32_e32 v188, v186, v187
	v_pk_mul_f32 v[158:159], v[228:229], v[184:185] op_sel_hi:[1,0]
	v_add_f32_e32 v192, v190, v191
	v_add_f32_dpp v188, v188, v188 quad_perm:[1,0,3,2] row_mask:0xf bank_mask:0xf bound_ctrl:1
	v_pk_mul_f32 v[182:183], v[230:231], v[184:185] op_sel_hi:[1,0]
	v_add_f32_dpp v192, v192, v192 quad_perm:[1,0,3,2] row_mask:0xf bank_mask:0xf bound_ctrl:1
	v_add_f32_dpp v188, v188, v188 quad_perm:[2,3,0,1] row_mask:0xf bank_mask:0xf bound_ctrl:1
	v_pk_fma_f32 v[194:195], v[32:33], v[220:221], v[158:159]
	ds_write_b32 v193, v192 offset:512
	v_add_f32_dpp v188, v188, v188 row_half_mirror row_mask:0xf bank_mask:0xf bound_ctrl:1
	v_pk_fma_f32 v[214:215], v[34:35], v[222:223], v[182:183]
	s_nop 0
	v_add_f32_dpp v188, v188, v188 row_mirror row_mask:0xf bank_mask:0xf bound_ctrl:1
	v_pk_fma_f32 v[32:33], v[224:225], v[188:189], v[194:195] op_sel_hi:[1,0,1]
	v_pk_fma_f32 v[34:35], v[226:227], v[188:189], v[214:215] op_sel_hi:[1,0,1]
	s_waitcnt lgkmcnt(8)
	v_pk_mul_f32 v[186:187], v[32:33], v[136:137]
	v_pk_mul_f32 v[190:191], v[32:33], v[232:233]
	v_pk_fma_f32 v[186:187], v[34:35], v[138:139], v[186:187]
	v_pk_fma_f32 v[190:191], v[34:35], v[234:235], v[190:191]
	ds_read_b128 v[216:219], v237 offset:6400
	ds_read_b128 v[220:223], v237 offset:6416
	ds_read_b128 v[224:227], v237 offset:6432
	ds_read_b128 v[228:231], v237 offset:6448
	ds_read_b128 v[232:235], v237 offset:6464
	ds_read_b32 v184, v238 offset:320
	v_add_f32_e32 v188, v186, v187
	v_pk_mul_f32 v[158:159], v[148:149], v[156:157] op_sel_hi:[1,0]
	v_add_f32_e32 v192, v190, v191
	v_add_f32_dpp v188, v188, v188 quad_perm:[1,0,3,2] row_mask:0xf bank_mask:0xf bound_ctrl:1
	v_pk_mul_f32 v[182:183], v[150:151], v[156:157] op_sel_hi:[1,0]
	v_add_f32_dpp v192, v192, v192 quad_perm:[1,0,3,2] row_mask:0xf bank_mask:0xf bound_ctrl:1
	v_add_f32_dpp v188, v188, v188 quad_perm:[2,3,0,1] row_mask:0xf bank_mask:0xf bound_ctrl:1
	v_pk_fma_f32 v[194:195], v[32:33], v[140:141], v[158:159]
	ds_write_b32 v193, v192 offset:1024
	v_add_f32_dpp v188, v188, v188 row_half_mirror row_mask:0xf bank_mask:0xf bound_ctrl:1
	v_pk_fma_f32 v[214:215], v[34:35], v[142:143], v[182:183]
	s_nop 0
	v_add_f32_dpp v188, v188, v188 row_mirror row_mask:0xf bank_mask:0xf bound_ctrl:1
	v_pk_fma_f32 v[32:33], v[144:145], v[188:189], v[194:195] op_sel_hi:[1,0,1]
	v_pk_fma_f32 v[34:35], v[146:147], v[188:189], v[214:215] op_sel_hi:[1,0,1]
	s_waitcnt lgkmcnt(8)
; DEVI void rwkv_scan_item(int TID_, int BID_, PREF p, int g, int item, char* shm) {
;     ...
;       for (int s = 0; s < TB; ++s) {
;         OpsR c = n1;
;         n1 = n2;
;         if (s + 2 < TB) n2 = ld(ob, vb, s + 2);
;         f2v a01 = {c.a.x, c.a.y}, a23 = {c.a.z, c.a.w}, w01 = {c.w.x, c.w.y}, w23 = {c.w.z, c.w.w},
;             b01 = {c.b.x, c.b.y}, b23 = {c.b.z, c.b.w}, k01 = {c.k.x, c.k.y}, k23 = {c.k.z, c.k.w},
;             r01 = {c.r.x, c.r.y}, r23 = {c.r.z, c.r.w};
;         f2v vv = {c.v, c.v};
;         f2v vk01 = vv * k01, vk23 = vv * k23;
;         f2v t = S01 * a01;
;         t = S23 * a23 + t;
;         float sa = allreduce16(t.x + t.y);
;         f2v sv = {sa, sa};
;         S01 = S01 * w01 + (sv * b01 + vk01);
;         S23 = S23 * w23 + (sv * b23 + vk23);
;         f2v u = S01 * r01;
;         u = S23 * r23 + u;
;         float uu = u.x + u.y;
;         uu += dppmov<0xB1>(uu);
;         yb[s * 128] = uu;
;       }
	v_pk_mul_f32 v[186:187], v[32:33], v[160:161]
	v_pk_mul_f32 v[190:191], v[32:33], v[152:153]
	v_pk_fma_f32 v[186:187], v[34:35], v[162:163], v[186:187]
	v_pk_fma_f32 v[190:191], v[34:35], v[154:155], v[190:191]
	ds_read_b128 v[136:139], v237 offset:7680
	ds_read_b128 v[140:143], v237 offset:7696
	ds_read_b128 v[144:147], v237 offset:7712
	ds_read_b128 v[148:151], v237 offset:7728
	ds_read_b128 v[152:155], v237 offset:7744
	ds_read_b32 v156, v238 offset:384
	v_add_f32_e32 v188, v186, v187
	v_pk_mul_f32 v[158:159], v[172:173], v[180:181] op_sel_hi:[1,0]
	v_add_f32_e32 v192, v190, v191
	v_add_f32_dpp v188, v188, v188 quad_perm:[1,0,3,2] row_mask:0xf bank_mask:0xf bound_ctrl:1
	v_pk_mul_f32 v[182:183], v[174:175], v[180:181] op_sel_hi:[1,0]
	v_add_f32_dpp v192, v192, v192 quad_perm:[1,0,3,2] row_mask:0xf bank_mask:0xf bound_ctrl:1
	v_add_f32_dpp v188, v188, v188 quad_perm:[2,3,0,1] row_mask:0xf bank_mask:0xf bound_ctrl:1
	v_pk_fma_f32 v[194:195], v[32:33], v[164:165], v[158:159]
	ds_write_b32 v193, v192 offset:1536
	v_add_f32_dpp v188, v188, v188 row_half_mirror row_mask:0xf bank_mask:0xf bound_ctrl:1
	v_pk_fma_f32 v[214:215], v[34:35], v[166:167], v[182:183]
	s_nop 0
	v_add_f32_dpp v188, v188, v188 row_mirror row_mask:0xf bank_mask:0xf bound_ctrl:1
	v_pk_fma_f32 v[32:33], v[168:169], v[188:189], v[194:195] op_sel_hi:[1,0,1]
	v_pk_fma_f32 v[34:35], v[170:171], v[188:189], v[214:215] op_sel_hi:[1,0,1]
	s_waitcnt lgkmcnt(8)
	v_pk_mul_f32 v[186:187], v[32:33], v[216:217]
	v_pk_mul_f32 v[190:191], v[32:33], v[176:177]
	v_pk_fma_f32 v[186:187], v[34:35], v[218:219], v[186:187]
	v_pk_fma_f32 v[190:191], v[34:35], v[178:179], v[190:191]
	ds_read_b128 v[160:163], v237 offset:8960
	ds_read_b128 v[164:167], v237 offset:8976
	ds_read_b128 v[168:171], v237 offset:8992
	ds_read_b128 v[172:175], v237 offset:9008
	ds_read_b128 v[176:179], v237 offset:9024
	ds_read_b32 v180, v238 offset:448
	v_add_f32_e32 v188, v186, v187
	v_pk_mul_f32 v[158:159], v[228:229], v[184:185] op_sel_hi:[1,0]
	v_add_f32_e32 v192, v190, v191
	v_add_f32_dpp v188, v188, v188 quad_perm:[1,0,3,2] row_mask:0xf bank_mask:0xf bound_ctrl:1
	v_pk_mul_f32 v[182:183], v[230:231], v[184:185] op_sel_hi:[1,0]
	v_add_f32_dpp v192, v192, v192 quad_perm:[1,0,3,2] row_mask:0xf bank_mask:0xf bound_ctrl:1
	v_add_f32_dpp v188, v188, v188 quad_perm:[2,3,0,1] row_mask:0xf bank_mask:0xf bound_ctrl:1
	v_pk_fma_f32 v[194:195], v[32:33], v[220:221], v[158:159]
	ds_write_b32 v193, v192 offset:2048
	v_add_f32_dpp v188, v188, v188 row_half_mirror row_mask:0xf bank_mask:0xf bound_ctrl:1
	v_pk_fma_f32 v[214:215], v[34:35], v[222:223], v[182:183]
	s_nop 0
	v_add_f32_dpp v188, v188, v188 row_mirror row_mask:0xf bank_mask:0xf bound_ctrl:1
	v_pk_fma_f32 v[32:33], v[224:225], v[188:189], v[194:195] op_sel_hi:[1,0,1]
	v_pk_fma_f32 v[34:35], v[226:227], v[188:189], v[214:215] op_sel_hi:[1,0,1]
	s_waitcnt lgkmcnt(8)
	v_pk_mul_f32 v[186:187], v[32:33], v[136:137]
	v_pk_mul_f32 v[190:191], v[32:33], v[232:233]
	v_pk_fma_f32 v[186:187], v[34:35], v[138:139], v[186:187]
	v_pk_fma_f32 v[190:191], v[34:35], v[234:235], v[190:191]
	ds_read_b128 v[216:219], v237 offset:10240
	ds_read_b128 v[220:223], v237 offset:10256
	ds_read_b128 v[224:227], v237 offset:10272
	ds_read_b128 v[228:231], v237 offset:10288
	ds_read_b128 v[232:235], v237 offset:10304
	ds_read_b32 v184, v238 offset:512
	v_add_f32_e32 v188, v186, v187
	v_pk_mul_f32 v[158:159], v[148:149], v[156:157] op_sel_hi:[1,0]
	v_add_f32_e32 v192, v190, v191
	v_add_f32_dpp v188, v188, v188 quad_perm:[1,0,3,2] row_mask:0xf bank_mask:0xf bound_ctrl:1
	v_pk_mul_f32 v[182:183], v[150:151], v[156:157] op_sel_hi:[1,0]
	v_add_f32_dpp v192, v192, v192 quad_perm:[1,0,3,2] row_mask:0xf bank_mask:0xf bound_ctrl:1
	v_add_f32_dpp v188, v188, v188 quad_perm:[2,3,0,1] row_mask:0xf bank_mask:0xf bound_ctrl:1
	v_pk_fma_f32 v[194:195], v[32:33], v[140:141], v[158:159]
	ds_write_b32 v193, v192 offset:2560
	v_add_f32_dpp v188, v188, v188 row_half_mirror row_mask:0xf bank_mask:0xf bound_ctrl:1
	v_pk_fma_f32 v[214:215], v[34:35], v[142:143], v[182:183]
	s_nop 0
	v_add_f32_dpp v188, v188, v188 row_mirror row_mask:0xf bank_mask:0xf bound_ctrl:1
	v_pk_fma_f32 v[32:33], v[144:145], v[188:189], v[194:195] op_sel_hi:[1,0,1]
	v_pk_fma_f32 v[34:35], v[146:147], v[188:189], v[214:215] op_sel_hi:[1,0,1]
	s_waitcnt lgkmcnt(8)
	v_pk_mul_f32 v[186:187], v[32:33], v[160:161]
	v_pk_mul_f32 v[190:191], v[32:33], v[152:153]
	v_pk_fma_f32 v[186:187], v[34:35], v[162:163], v[186:187]
	v_pk_fma_f32 v[190:191], v[34:35], v[154:155], v[190:191]
	ds_read_b128 v[136:139], v237 offset:11520
	ds_read_b128 v[140:143], v237 offset:11536
	ds_read_b128 v[144:147], v237 offset:11552
	ds_read_b128 v[148:151], v237 offset:11568
	ds_read_b128 v[152:155], v237 offset:11584
	ds_read_b32 v156, v238 offset:576
	v_add_f32_e32 v188, v186, v187
	v_pk_mul_f32 v[158:159], v[172:173], v[180:181] op_sel_hi:[1,0]
	v_add_f32_e32 v192, v190, v191
	v_add_f32_dpp v188, v188, v188 quad_perm:[1,0,3,2] row_mask:0xf bank_mask:0xf bound_ctrl:1
	v_pk_mul_f32 v[182:183], v[174:175], v[180:181] op_sel_hi:[1,0]
	v_add_f32_dpp v192, v192, v192 quad_perm:[1,0,3,2] row_mask:0xf bank_mask:0xf bound_ctrl:1
	v_add_f32_dpp v188, v188, v188 quad_perm:[2,3,0,1] row_mask:0xf bank_mask:0xf bound_ctrl:1
	v_pk_fma_f32 v[194:195], v[32:33], v[164:165], v[158:159]
	ds_write_b32 v193, v192 offset:3072
	v_add_f32_dpp v188, v188, v188 row_half_mirror row_mask:0xf bank_mask:0xf bound_ctrl:1
	v_pk_fma_f32 v[214:215], v[34:35], v[166:167], v[182:183]
	s_nop 0
	v_add_f32_dpp v188, v188, v188 row_mirror row_mask:0xf bank_mask:0xf bound_ctrl:1
	v_pk_fma_f32 v[32:33], v[168:169], v[188:189], v[194:195] op_sel_hi:[1,0,1]
	v_pk_fma_f32 v[34:35], v[170:171], v[188:189], v[214:215] op_sel_hi:[1,0,1]
	s_waitcnt lgkmcnt(8)
; DEVI void rwkv_scan_item(int TID_, int BID_, PREF p, int g, int item, char* shm) {
;     ...
;       for (int s = 0; s < TB; ++s) {
;         OpsR c = n1;
;         n1 = n2;
;         if (s + 2 < TB) n2 = ld(ob, vb, s + 2);
;         f2v a01 = {c.a.x, c.a.y}, a23 = {c.a.z, c.a.w}, w01 = {c.w.x, c.w.y}, w23 = {c.w.z, c.w.w},
;             b01 = {c.b.x, c.b.y}, b23 = {c.b.z, c.b.w}, k01 = {c.k.x, c.k.y}, k23 = {c.k.z, c.k.w},
;             r01 = {c.r.x, c.r.y}, r23 = {c.r.z, c.r.w};
;         f2v vv = {c.v, c.v};
;         f2v vk01 = vv * k01, vk23 = vv * k23;
;         f2v t = S01 * a01;
;         t = S23 * a23 + t;
;         float sa = allreduce16(t.x + t.y);
;         f2v sv = {sa, sa};
;         S01 = S01 * w01 + (sv * b01 + vk01);
;         S23 = S23 * w23 + (sv * b23 + vk23);
;         f2v u = S01 * r01;
;         u = S23 * r23 + u;
;         float uu = u.x + u.y;
;         uu += dppmov<0xB1>(uu);
;         yb[s * 128] = uu;
;       }
	v_pk_mul_f32 v[186:187], v[32:33], v[216:217]
	v_pk_mul_f32 v[190:191], v[32:33], v[176:177]
	v_pk_fma_f32 v[186:187], v[34:35], v[218:219], v[186:187]
	v_pk_fma_f32 v[190:191], v[34:35], v[178:179], v[190:191]
	ds_read_b128 v[160:163], v237 offset:12800
	ds_read_b128 v[164:167], v237 offset:12816
	ds_read_b128 v[168:171], v237 offset:12832
	ds_read_b128 v[172:175], v237 offset:12848
	ds_read_b128 v[176:179], v237 offset:12864
	ds_read_b32 v180, v238 offset:640
	v_add_f32_e32 v188, v186, v187
	v_pk_mul_f32 v[158:159], v[228:229], v[184:185] op_sel_hi:[1,0]
	v_add_f32_e32 v192, v190, v191
	v_add_f32_dpp v188, v188, v188 quad_perm:[1,0,3,2] row_mask:0xf bank_mask:0xf bound_ctrl:1
	v_pk_mul_f32 v[182:183], v[230:231], v[184:185] op_sel_hi:[1,0]
	v_add_f32_dpp v192, v192, v192 quad_perm:[1,0,3,2] row_mask:0xf bank_mask:0xf bound_ctrl:1
	v_add_f32_dpp v188, v188, v188 quad_perm:[2,3,0,1] row_mask:0xf bank_mask:0xf bound_ctrl:1
	v_pk_fma_f32 v[194:195], v[32:33], v[220:221], v[158:159]
	ds_write_b32 v193, v192 offset:3584
	v_add_f32_dpp v188, v188, v188 row_half_mirror row_mask:0xf bank_mask:0xf bound_ctrl:1
	v_pk_fma_f32 v[214:215], v[34:35], v[222:223], v[182:183]
	s_nop 0
	v_add_f32_dpp v188, v188, v188 row_mirror row_mask:0xf bank_mask:0xf bound_ctrl:1
	v_pk_fma_f32 v[32:33], v[224:225], v[188:189], v[194:195] op_sel_hi:[1,0,1]
	v_pk_fma_f32 v[34:35], v[226:227], v[188:189], v[214:215] op_sel_hi:[1,0,1]
	s_waitcnt lgkmcnt(8)
	v_pk_mul_f32 v[186:187], v[32:33], v[136:137]
	v_pk_mul_f32 v[190:191], v[32:33], v[232:233]
	v_pk_fma_f32 v[186:187], v[34:35], v[138:139], v[186:187]
	v_pk_fma_f32 v[190:191], v[34:35], v[234:235], v[190:191]
	ds_read_b128 v[216:219], v237 offset:14080
	ds_read_b128 v[220:223], v237 offset:14096
	ds_read_b128 v[224:227], v237 offset:14112
	ds_read_b128 v[228:231], v237 offset:14128
	ds_read_b128 v[232:235], v237 offset:14144
	ds_read_b32 v184, v238 offset:704
	v_add_f32_e32 v188, v186, v187
	v_pk_mul_f32 v[158:159], v[148:149], v[156:157] op_sel_hi:[1,0]
	v_add_f32_e32 v192, v190, v191
	v_add_f32_dpp v188, v188, v188 quad_perm:[1,0,3,2] row_mask:0xf bank_mask:0xf bound_ctrl:1
	v_pk_mul_f32 v[182:183], v[150:151], v[156:157] op_sel_hi:[1,0]
	v_add_f32_dpp v192, v192, v192 quad_perm:[1,0,3,2] row_mask:0xf bank_mask:0xf bound_ctrl:1
	v_add_f32_dpp v188, v188, v188 quad_perm:[2,3,0,1] row_mask:0xf bank_mask:0xf bound_ctrl:1
	v_pk_fma_f32 v[194:195], v[32:33], v[140:141], v[158:159]
	ds_write_b32 v193, v192 offset:4096
	v_add_f32_dpp v188, v188, v188 row_half_mirror row_mask:0xf bank_mask:0xf bound_ctrl:1
	v_pk_fma_f32 v[214:215], v[34:35], v[142:143], v[182:183]
	s_nop 0
	v_add_f32_dpp v188, v188, v188 row_mirror row_mask:0xf bank_mask:0xf bound_ctrl:1
	v_pk_fma_f32 v[32:33], v[144:145], v[188:189], v[194:195] op_sel_hi:[1,0,1]
	v_pk_fma_f32 v[34:35], v[146:147], v[188:189], v[214:215] op_sel_hi:[1,0,1]
	s_waitcnt lgkmcnt(8)
	v_pk_mul_f32 v[186:187], v[32:33], v[160:161]
	v_pk_mul_f32 v[190:191], v[32:33], v[152:153]
	v_pk_fma_f32 v[186:187], v[34:35], v[162:163], v[186:187]
	v_pk_fma_f32 v[190:191], v[34:35], v[154:155], v[190:191]
	ds_read_b128 v[136:139], v237 offset:15360
	ds_read_b128 v[140:143], v237 offset:15376
	ds_read_b128 v[144:147], v237 offset:15392
	ds_read_b128 v[148:151], v237 offset:15408
	ds_read_b128 v[152:155], v237 offset:15424
	ds_read_b32 v156, v238 offset:768
	v_add_f32_e32 v188, v186, v187
	v_pk_mul_f32 v[158:159], v[172:173], v[180:181] op_sel_hi:[1,0]
	v_add_f32_e32 v192, v190, v191
	v_add_f32_dpp v188, v188, v188 quad_perm:[1,0,3,2] row_mask:0xf bank_mask:0xf bound_ctrl:1
	v_pk_mul_f32 v[182:183], v[174:175], v[180:181] op_sel_hi:[1,0]
	v_add_f32_dpp v192, v192, v192 quad_perm:[1,0,3,2] row_mask:0xf bank_mask:0xf bound_ctrl:1
	v_add_f32_dpp v188, v188, v188 quad_perm:[2,3,0,1] row_mask:0xf bank_mask:0xf bound_ctrl:1
	v_pk_fma_f32 v[194:195], v[32:33], v[164:165], v[158:159]
	ds_write_b32 v193, v192 offset:4608
	v_add_f32_dpp v188, v188, v188 row_half_mirror row_mask:0xf bank_mask:0xf bound_ctrl:1
	v_pk_fma_f32 v[214:215], v[34:35], v[166:167], v[182:183]
	s_nop 0
	v_add_f32_dpp v188, v188, v188 row_mirror row_mask:0xf bank_mask:0xf bound_ctrl:1
	v_pk_fma_f32 v[32:33], v[168:169], v[188:189], v[194:195] op_sel_hi:[1,0,1]
	v_pk_fma_f32 v[34:35], v[170:171], v[188:189], v[214:215] op_sel_hi:[1,0,1]
	s_waitcnt lgkmcnt(8)
	v_pk_mul_f32 v[186:187], v[32:33], v[216:217]
	v_pk_mul_f32 v[190:191], v[32:33], v[176:177]
	v_pk_fma_f32 v[186:187], v[34:35], v[218:219], v[186:187]
	v_pk_fma_f32 v[190:191], v[34:35], v[178:179], v[190:191]
	ds_read_b128 v[160:163], v237 offset:16640
	ds_read_b128 v[164:167], v237 offset:16656
	ds_read_b128 v[168:171], v237 offset:16672
	ds_read_b128 v[172:175], v237 offset:16688
	ds_read_b128 v[176:179], v237 offset:16704
	ds_read_b32 v180, v238 offset:832
	v_add_f32_e32 v188, v186, v187
	v_pk_mul_f32 v[158:159], v[228:229], v[184:185] op_sel_hi:[1,0]
	v_add_f32_e32 v192, v190, v191
	v_add_f32_dpp v188, v188, v188 quad_perm:[1,0,3,2] row_mask:0xf bank_mask:0xf bound_ctrl:1
	v_pk_mul_f32 v[182:183], v[230:231], v[184:185] op_sel_hi:[1,0]
	v_add_f32_dpp v192, v192, v192 quad_perm:[1,0,3,2] row_mask:0xf bank_mask:0xf bound_ctrl:1
	v_add_f32_dpp v188, v188, v188 quad_perm:[2,3,0,1] row_mask:0xf bank_mask:0xf bound_ctrl:1
	v_pk_fma_f32 v[194:195], v[32:33], v[220:221], v[158:159]
	ds_write_b32 v193, v192 offset:5120
	v_add_f32_dpp v188, v188, v188 row_half_mirror row_mask:0xf bank_mask:0xf bound_ctrl:1
	v_pk_fma_f32 v[214:215], v[34:35], v[222:223], v[182:183]
	s_nop 0
	v_add_f32_dpp v188, v188, v188 row_mirror row_mask:0xf bank_mask:0xf bound_ctrl:1
	v_pk_fma_f32 v[32:33], v[224:225], v[188:189], v[194:195] op_sel_hi:[1,0,1]
	v_pk_fma_f32 v[34:35], v[226:227], v[188:189], v[214:215] op_sel_hi:[1,0,1]
	s_waitcnt lgkmcnt(8)
; DEVI void rwkv_scan_item(int TID_, int BID_, PREF p, int g, int item, char* shm) {
;     ...
;       for (int s = 0; s < TB; ++s) {
;         OpsR c = n1;
;         n1 = n2;
;         if (s + 2 < TB) n2 = ld(ob, vb, s + 2);
;         f2v a01 = {c.a.x, c.a.y}, a23 = {c.a.z, c.a.w}, w01 = {c.w.x, c.w.y}, w23 = {c.w.z, c.w.w},
;             b01 = {c.b.x, c.b.y}, b23 = {c.b.z, c.b.w}, k01 = {c.k.x, c.k.y}, k23 = {c.k.z, c.k.w},
;             r01 = {c.r.x, c.r.y}, r23 = {c.r.z, c.r.w};
;         f2v vv = {c.v, c.v};
;         f2v vk01 = vv * k01, vk23 = vv * k23;
;         f2v t = S01 * a01;
;         t = S23 * a23 + t;
;         float sa = allreduce16(t.x + t.y);
;         f2v sv = {sa, sa};
;         S01 = S01 * w01 + (sv * b01 + vk01);
;         S23 = S23 * w23 + (sv * b23 + vk23);
;         f2v u = S01 * r01;
;         u = S23 * r23 + u;
;         float uu = u.x + u.y;
;         uu += dppmov<0xB1>(uu);
;         yb[s * 128] = uu;
;       }
	v_pk_mul_f32 v[186:187], v[32:33], v[136:137]
	v_pk_mul_f32 v[190:191], v[32:33], v[232:233]
	v_pk_fma_f32 v[186:187], v[34:35], v[138:139], v[186:187]
	v_pk_fma_f32 v[190:191], v[34:35], v[234:235], v[190:191]
	ds_read_b128 v[216:219], v237 offset:17920
	ds_read_b128 v[220:223], v237 offset:17936
	ds_read_b128 v[224:227], v237 offset:17952
	ds_read_b128 v[228:231], v237 offset:17968
	ds_read_b128 v[232:235], v237 offset:17984
	ds_read_b32 v184, v238 offset:896
	v_add_f32_e32 v188, v186, v187
	v_pk_mul_f32 v[158:159], v[148:149], v[156:157] op_sel_hi:[1,0]
	v_add_f32_e32 v192, v190, v191
	v_add_f32_dpp v188, v188, v188 quad_perm:[1,0,3,2] row_mask:0xf bank_mask:0xf bound_ctrl:1
	v_pk_mul_f32 v[182:183], v[150:151], v[156:157] op_sel_hi:[1,0]
	v_add_f32_dpp v192, v192, v192 quad_perm:[1,0,3,2] row_mask:0xf bank_mask:0xf bound_ctrl:1
	v_add_f32_dpp v188, v188, v188 quad_perm:[2,3,0,1] row_mask:0xf bank_mask:0xf bound_ctrl:1
	v_pk_fma_f32 v[194:195], v[32:33], v[140:141], v[158:159]
	ds_write_b32 v193, v192 offset:5632
	v_add_f32_dpp v188, v188, v188 row_half_mirror row_mask:0xf bank_mask:0xf bound_ctrl:1
	v_pk_fma_f32 v[214:215], v[34:35], v[142:143], v[182:183]
	s_nop 0
	v_add_f32_dpp v188, v188, v188 row_mirror row_mask:0xf bank_mask:0xf bound_ctrl:1
	v_pk_fma_f32 v[32:33], v[144:145], v[188:189], v[194:195] op_sel_hi:[1,0,1]
	v_pk_fma_f32 v[34:35], v[146:147], v[188:189], v[214:215] op_sel_hi:[1,0,1]
	s_waitcnt lgkmcnt(8)
	v_pk_mul_f32 v[186:187], v[32:33], v[160:161]
	v_pk_mul_f32 v[190:191], v[32:33], v[152:153]
	v_pk_fma_f32 v[186:187], v[34:35], v[162:163], v[186:187]
	v_pk_fma_f32 v[190:191], v[34:35], v[154:155], v[190:191]
	ds_read_b128 v[136:139], v237 offset:19200
	ds_read_b128 v[140:143], v237 offset:19216
	ds_read_b128 v[144:147], v237 offset:19232
	ds_read_b128 v[148:151], v237 offset:19248
	ds_read_b128 v[152:155], v237 offset:19264
	ds_read_b32 v156, v238 offset:960
	v_add_f32_e32 v188, v186, v187
	v_pk_mul_f32 v[158:159], v[172:173], v[180:181] op_sel_hi:[1,0]
	v_add_f32_e32 v192, v190, v191
	v_add_f32_dpp v188, v188, v188 quad_perm:[1,0,3,2] row_mask:0xf bank_mask:0xf bound_ctrl:1
	v_pk_mul_f32 v[182:183], v[174:175], v[180:181] op_sel_hi:[1,0]
	v_add_f32_dpp v192, v192, v192 quad_perm:[1,0,3,2] row_mask:0xf bank_mask:0xf bound_ctrl:1
	v_add_f32_dpp v188, v188, v188 quad_perm:[2,3,0,1] row_mask:0xf bank_mask:0xf bound_ctrl:1
	v_pk_fma_f32 v[194:195], v[32:33], v[164:165], v[158:159]
	ds_write_b32 v193, v192 offset:6144
	v_add_f32_dpp v188, v188, v188 row_half_mirror row_mask:0xf bank_mask:0xf bound_ctrl:1
	v_pk_fma_f32 v[214:215], v[34:35], v[166:167], v[182:183]
	s_nop 0
	v_add_f32_dpp v188, v188, v188 row_mirror row_mask:0xf bank_mask:0xf bound_ctrl:1
	v_pk_fma_f32 v[32:33], v[168:169], v[188:189], v[194:195] op_sel_hi:[1,0,1]
	v_pk_fma_f32 v[34:35], v[170:171], v[188:189], v[214:215] op_sel_hi:[1,0,1]
	s_waitcnt lgkmcnt(8)
	v_pk_mul_f32 v[186:187], v[32:33], v[216:217]
	v_pk_mul_f32 v[190:191], v[32:33], v[176:177]
	v_pk_fma_f32 v[186:187], v[34:35], v[218:219], v[186:187]
	v_pk_fma_f32 v[190:191], v[34:35], v[178:179], v[190:191]
	ds_read_b128 v[160:163], v237 offset:20480
	ds_read_b128 v[164:167], v237 offset:20496
	ds_read_b128 v[168:171], v237 offset:20512
	ds_read_b128 v[172:175], v237 offset:20528
	ds_read_b128 v[176:179], v237 offset:20544
	ds_read_b32 v180, v238 offset:1024
	v_add_f32_e32 v188, v186, v187
	v_pk_mul_f32 v[158:159], v[228:229], v[184:185] op_sel_hi:[1,0]
	v_add_f32_e32 v192, v190, v191
	v_add_f32_dpp v188, v188, v188 quad_perm:[1,0,3,2] row_mask:0xf bank_mask:0xf bound_ctrl:1
	v_pk_mul_f32 v[182:183], v[230:231], v[184:185] op_sel_hi:[1,0]
	v_add_f32_dpp v192, v192, v192 quad_perm:[1,0,3,2] row_mask:0xf bank_mask:0xf bound_ctrl:1
	v_add_f32_dpp v188, v188, v188 quad_perm:[2,3,0,1] row_mask:0xf bank_mask:0xf bound_ctrl:1
	v_pk_fma_f32 v[194:195], v[32:33], v[220:221], v[158:159]
	ds_write_b32 v193, v192 offset:6656
	v_add_f32_dpp v188, v188, v188 row_half_mirror row_mask:0xf bank_mask:0xf bound_ctrl:1
	v_pk_fma_f32 v[214:215], v[34:35], v[222:223], v[182:183]
	s_nop 0
	v_add_f32_dpp v188, v188, v188 row_mirror row_mask:0xf bank_mask:0xf bound_ctrl:1
	v_pk_fma_f32 v[32:33], v[224:225], v[188:189], v[194:195] op_sel_hi:[1,0,1]
	v_pk_fma_f32 v[34:35], v[226:227], v[188:189], v[214:215] op_sel_hi:[1,0,1]
	s_waitcnt lgkmcnt(8)
	v_pk_mul_f32 v[186:187], v[32:33], v[136:137]
	v_pk_mul_f32 v[190:191], v[32:33], v[232:233]
	v_pk_fma_f32 v[186:187], v[34:35], v[138:139], v[186:187]
	v_pk_fma_f32 v[190:191], v[34:35], v[234:235], v[190:191]
	ds_read_b128 v[216:219], v237 offset:21760
	ds_read_b128 v[220:223], v237 offset:21776
	ds_read_b128 v[224:227], v237 offset:21792
	ds_read_b128 v[228:231], v237 offset:21808
	ds_read_b128 v[232:235], v237 offset:21824
	ds_read_b32 v184, v238 offset:1088
	v_add_f32_e32 v188, v186, v187
	v_pk_mul_f32 v[158:159], v[148:149], v[156:157] op_sel_hi:[1,0]
	v_add_f32_e32 v192, v190, v191
	v_add_f32_dpp v188, v188, v188 quad_perm:[1,0,3,2] row_mask:0xf bank_mask:0xf bound_ctrl:1
	v_pk_mul_f32 v[182:183], v[150:151], v[156:157] op_sel_hi:[1,0]
	v_add_f32_dpp v192, v192, v192 quad_perm:[1,0,3,2] row_mask:0xf bank_mask:0xf bound_ctrl:1
	v_add_f32_dpp v188, v188, v188 quad_perm:[2,3,0,1] row_mask:0xf bank_mask:0xf bound_ctrl:1
	v_pk_fma_f32 v[194:195], v[32:33], v[140:141], v[158:159]
	ds_write_b32 v193, v192 offset:7168
	v_add_f32_dpp v188, v188, v188 row_half_mirror row_mask:0xf bank_mask:0xf bound_ctrl:1
	v_pk_fma_f32 v[214:215], v[34:35], v[142:143], v[182:183]
	s_nop 0
	v_add_f32_dpp v188, v188, v188 row_mirror row_mask:0xf bank_mask:0xf bound_ctrl:1
	v_pk_fma_f32 v[32:33], v[144:145], v[188:189], v[194:195] op_sel_hi:[1,0,1]
	v_pk_fma_f32 v[34:35], v[146:147], v[188:189], v[214:215] op_sel_hi:[1,0,1]
	s_waitcnt lgkmcnt(8)
; DEVI void rwkv_scan_item(int TID_, int BID_, PREF p, int g, int item, char* shm) {
;     ...
;       for (int s = 0; s < TB; ++s) {
;         OpsR c = n1;
;         n1 = n2;
;         if (s + 2 < TB) n2 = ld(ob, vb, s + 2);
;         f2v a01 = {c.a.x, c.a.y}, a23 = {c.a.z, c.a.w}, w01 = {c.w.x, c.w.y}, w23 = {c.w.z, c.w.w},
;             b01 = {c.b.x, c.b.y}, b23 = {c.b.z, c.b.w}, k01 = {c.k.x, c.k.y}, k23 = {c.k.z, c.k.w},
;             r01 = {c.r.x, c.r.y}, r23 = {c.r.z, c.r.w};
;         f2v vv = {c.v, c.v};
;         f2v vk01 = vv * k01, vk23 = vv * k23;
;         f2v t = S01 * a01;
;         t = S23 * a23 + t;
;         float sa = allreduce16(t.x + t.y);
;         f2v sv = {sa, sa};
;         S01 = S01 * w01 + (sv * b01 + vk01);
;         S23 = S23 * w23 + (sv * b23 + vk23);
;         f2v u = S01 * r01;
;         u = S23 * r23 + u;
;         float uu = u.x + u.y;
;         uu += dppmov<0xB1>(uu);
;         yb[s * 128] = uu;
;       }
	v_pk_mul_f32 v[186:187], v[32:33], v[160:161]
	v_pk_mul_f32 v[190:191], v[32:33], v[152:153]
	v_pk_fma_f32 v[186:187], v[34:35], v[162:163], v[186:187]
	v_pk_fma_f32 v[190:191], v[34:35], v[154:155], v[190:191]
	ds_read_b128 v[136:139], v237 offset:23040
	ds_read_b128 v[140:143], v237 offset:23056
	ds_read_b128 v[144:147], v237 offset:23072
	ds_read_b128 v[148:151], v237 offset:23088
	ds_read_b128 v[152:155], v237 offset:23104
	ds_read_b32 v156, v238 offset:1152
	v_add_f32_e32 v188, v186, v187
	v_pk_mul_f32 v[158:159], v[172:173], v[180:181] op_sel_hi:[1,0]
	v_add_f32_e32 v192, v190, v191
	v_add_f32_dpp v188, v188, v188 quad_perm:[1,0,3,2] row_mask:0xf bank_mask:0xf bound_ctrl:1
	v_pk_mul_f32 v[182:183], v[174:175], v[180:181] op_sel_hi:[1,0]
	v_add_f32_dpp v192, v192, v192 quad_perm:[1,0,3,2] row_mask:0xf bank_mask:0xf bound_ctrl:1
	v_add_f32_dpp v188, v188, v188 quad_perm:[2,3,0,1] row_mask:0xf bank_mask:0xf bound_ctrl:1
	v_pk_fma_f32 v[194:195], v[32:33], v[164:165], v[158:159]
	ds_write_b32 v193, v192 offset:7680
	v_add_f32_dpp v188, v188, v188 row_half_mirror row_mask:0xf bank_mask:0xf bound_ctrl:1
	v_pk_fma_f32 v[214:215], v[34:35], v[166:167], v[182:183]
	s_nop 0
	v_add_f32_dpp v188, v188, v188 row_mirror row_mask:0xf bank_mask:0xf bound_ctrl:1
	v_pk_fma_f32 v[32:33], v[168:169], v[188:189], v[194:195] op_sel_hi:[1,0,1]
	v_pk_fma_f32 v[34:35], v[170:171], v[188:189], v[214:215] op_sel_hi:[1,0,1]
	s_waitcnt lgkmcnt(8)
	v_pk_mul_f32 v[186:187], v[32:33], v[216:217]
	v_pk_mul_f32 v[190:191], v[32:33], v[176:177]
	v_pk_fma_f32 v[186:187], v[34:35], v[218:219], v[186:187]
	v_pk_fma_f32 v[190:191], v[34:35], v[178:179], v[190:191]
	ds_read_b128 v[160:163], v237 offset:24320
	ds_read_b128 v[164:167], v237 offset:24336
	ds_read_b128 v[168:171], v237 offset:24352
	ds_read_b128 v[172:175], v237 offset:24368
	ds_read_b128 v[176:179], v237 offset:24384
	ds_read_b32 v180, v238 offset:1216
	v_add_f32_e32 v188, v186, v187
	v_pk_mul_f32 v[158:159], v[228:229], v[184:185] op_sel_hi:[1,0]
	v_add_f32_e32 v192, v190, v191
	v_add_f32_dpp v188, v188, v188 quad_perm:[1,0,3,2] row_mask:0xf bank_mask:0xf bound_ctrl:1
	v_pk_mul_f32 v[182:183], v[230:231], v[184:185] op_sel_hi:[1,0]
	v_add_f32_dpp v192, v192, v192 quad_perm:[1,0,3,2] row_mask:0xf bank_mask:0xf bound_ctrl:1
	v_add_f32_dpp v188, v188, v188 quad_perm:[2,3,0,1] row_mask:0xf bank_mask:0xf bound_ctrl:1
	v_pk_fma_f32 v[194:195], v[32:33], v[220:221], v[158:159]
	ds_write_b32 v193, v192 offset:8192
	v_add_f32_dpp v188, v188, v188 row_half_mirror row_mask:0xf bank_mask:0xf bound_ctrl:1
	v_pk_fma_f32 v[214:215], v[34:35], v[222:223], v[182:183]
	s_nop 0
	v_add_f32_dpp v188, v188, v188 row_mirror row_mask:0xf bank_mask:0xf bound_ctrl:1
	v_pk_fma_f32 v[32:33], v[224:225], v[188:189], v[194:195] op_sel_hi:[1,0,1]
	v_pk_fma_f32 v[34:35], v[226:227], v[188:189], v[214:215] op_sel_hi:[1,0,1]
	s_waitcnt lgkmcnt(8)
	v_pk_mul_f32 v[186:187], v[32:33], v[136:137]
	v_pk_mul_f32 v[190:191], v[32:33], v[232:233]
	v_pk_fma_f32 v[186:187], v[34:35], v[138:139], v[186:187]
	v_pk_fma_f32 v[190:191], v[34:35], v[234:235], v[190:191]
	ds_read_b128 v[216:219], v237 offset:25600
	ds_read_b128 v[220:223], v237 offset:25616
	ds_read_b128 v[224:227], v237 offset:25632
	ds_read_b128 v[228:231], v237 offset:25648
	ds_read_b128 v[232:235], v237 offset:25664
	ds_read_b32 v184, v238 offset:1280
	v_add_f32_e32 v188, v186, v187
	v_pk_mul_f32 v[158:159], v[148:149], v[156:157] op_sel_hi:[1,0]
	v_add_f32_e32 v192, v190, v191
	v_add_f32_dpp v188, v188, v188 quad_perm:[1,0,3,2] row_mask:0xf bank_mask:0xf bound_ctrl:1
	v_pk_mul_f32 v[182:183], v[150:151], v[156:157] op_sel_hi:[1,0]
	v_add_f32_dpp v192, v192, v192 quad_perm:[1,0,3,2] row_mask:0xf bank_mask:0xf bound_ctrl:1
	v_add_f32_dpp v188, v188, v188 quad_perm:[2,3,0,1] row_mask:0xf bank_mask:0xf bound_ctrl:1
	v_pk_fma_f32 v[194:195], v[32:33], v[140:141], v[158:159]
	ds_write_b32 v193, v192 offset:8704
	v_add_f32_dpp v188, v188, v188 row_half_mirror row_mask:0xf bank_mask:0xf bound_ctrl:1
	v_pk_fma_f32 v[214:215], v[34:35], v[142:143], v[182:183]
	s_nop 0
	v_add_f32_dpp v188, v188, v188 row_mirror row_mask:0xf bank_mask:0xf bound_ctrl:1
	v_pk_fma_f32 v[32:33], v[144:145], v[188:189], v[194:195] op_sel_hi:[1,0,1]
	v_pk_fma_f32 v[34:35], v[146:147], v[188:189], v[214:215] op_sel_hi:[1,0,1]
	s_waitcnt lgkmcnt(8)
	v_pk_mul_f32 v[186:187], v[32:33], v[160:161]
	v_pk_mul_f32 v[190:191], v[32:33], v[152:153]
	v_pk_fma_f32 v[186:187], v[34:35], v[162:163], v[186:187]
	v_pk_fma_f32 v[190:191], v[34:35], v[154:155], v[190:191]
	ds_read_b128 v[136:139], v237 offset:26880
	ds_read_b128 v[140:143], v237 offset:26896
	ds_read_b128 v[144:147], v237 offset:26912
	ds_read_b128 v[148:151], v237 offset:26928
	ds_read_b128 v[152:155], v237 offset:26944
	ds_read_b32 v156, v238 offset:1344
	v_add_f32_e32 v188, v186, v187
	v_pk_mul_f32 v[158:159], v[172:173], v[180:181] op_sel_hi:[1,0]
	v_add_f32_e32 v192, v190, v191
	v_add_f32_dpp v188, v188, v188 quad_perm:[1,0,3,2] row_mask:0xf bank_mask:0xf bound_ctrl:1
	v_pk_mul_f32 v[182:183], v[174:175], v[180:181] op_sel_hi:[1,0]
	v_add_f32_dpp v192, v192, v192 quad_perm:[1,0,3,2] row_mask:0xf bank_mask:0xf bound_ctrl:1
	v_add_f32_dpp v188, v188, v188 quad_perm:[2,3,0,1] row_mask:0xf bank_mask:0xf bound_ctrl:1
	v_pk_fma_f32 v[194:195], v[32:33], v[164:165], v[158:159]
	ds_write_b32 v193, v192 offset:9216
	v_add_f32_dpp v188, v188, v188 row_half_mirror row_mask:0xf bank_mask:0xf bound_ctrl:1
	v_pk_fma_f32 v[214:215], v[34:35], v[166:167], v[182:183]
	s_nop 0
	v_add_f32_dpp v188, v188, v188 row_mirror row_mask:0xf bank_mask:0xf bound_ctrl:1
	v_pk_fma_f32 v[32:33], v[168:169], v[188:189], v[194:195] op_sel_hi:[1,0,1]
	v_pk_fma_f32 v[34:35], v[170:171], v[188:189], v[214:215] op_sel_hi:[1,0,1]
	s_waitcnt lgkmcnt(8)
; DEVI void rwkv_scan_item(int TID_, int BID_, PREF p, int g, int item, char* shm) {
;     ...
;       for (int s = 0; s < TB; ++s) {
;         OpsR c = n1;
;         n1 = n2;
;         if (s + 2 < TB) n2 = ld(ob, vb, s + 2);
;         f2v a01 = {c.a.x, c.a.y}, a23 = {c.a.z, c.a.w}, w01 = {c.w.x, c.w.y}, w23 = {c.w.z, c.w.w},
;             b01 = {c.b.x, c.b.y}, b23 = {c.b.z, c.b.w}, k01 = {c.k.x, c.k.y}, k23 = {c.k.z, c.k.w},
;             r01 = {c.r.x, c.r.y}, r23 = {c.r.z, c.r.w};
;         f2v vv = {c.v, c.v};
;         f2v vk01 = vv * k01, vk23 = vv * k23;
;         f2v t = S01 * a01;
;         t = S23 * a23 + t;
;         float sa = allreduce16(t.x + t.y);
;         f2v sv = {sa, sa};
;         S01 = S01 * w01 + (sv * b01 + vk01);
;         S23 = S23 * w23 + (sv * b23 + vk23);
;         f2v u = S01 * r01;
;         u = S23 * r23 + u;
;         float uu = u.x + u.y;
;         uu += dppmov<0xB1>(uu);
;         yb[s * 128] = uu;
;       }
	v_pk_mul_f32 v[186:187], v[32:33], v[216:217]
	v_pk_mul_f32 v[190:191], v[32:33], v[176:177]
	v_pk_fma_f32 v[186:187], v[34:35], v[218:219], v[186:187]
	v_pk_fma_f32 v[190:191], v[34:35], v[178:179], v[190:191]
	ds_read_b128 v[160:163], v237 offset:28160
	ds_read_b128 v[164:167], v237 offset:28176
	ds_read_b128 v[168:171], v237 offset:28192
	ds_read_b128 v[172:175], v237 offset:28208
	ds_read_b128 v[176:179], v237 offset:28224
	ds_read_b32 v180, v238 offset:1408
	v_add_f32_e32 v188, v186, v187
	v_pk_mul_f32 v[158:159], v[228:229], v[184:185] op_sel_hi:[1,0]
	v_add_f32_e32 v192, v190, v191
	v_add_f32_dpp v188, v188, v188 quad_perm:[1,0,3,2] row_mask:0xf bank_mask:0xf bound_ctrl:1
	v_pk_mul_f32 v[182:183], v[230:231], v[184:185] op_sel_hi:[1,0]
	v_add_f32_dpp v192, v192, v192 quad_perm:[1,0,3,2] row_mask:0xf bank_mask:0xf bound_ctrl:1
	v_add_f32_dpp v188, v188, v188 quad_perm:[2,3,0,1] row_mask:0xf bank_mask:0xf bound_ctrl:1
	v_pk_fma_f32 v[194:195], v[32:33], v[220:221], v[158:159]
	ds_write_b32 v193, v192 offset:9728
	v_add_f32_dpp v188, v188, v188 row_half_mirror row_mask:0xf bank_mask:0xf bound_ctrl:1
	v_pk_fma_f32 v[214:215], v[34:35], v[222:223], v[182:183]
	s_nop 0
	v_add_f32_dpp v188, v188, v188 row_mirror row_mask:0xf bank_mask:0xf bound_ctrl:1
	v_pk_fma_f32 v[32:33], v[224:225], v[188:189], v[194:195] op_sel_hi:[1,0,1]
	v_pk_fma_f32 v[34:35], v[226:227], v[188:189], v[214:215] op_sel_hi:[1,0,1]
	s_waitcnt lgkmcnt(8)
	v_pk_mul_f32 v[186:187], v[32:33], v[136:137]
	v_pk_mul_f32 v[190:191], v[32:33], v[232:233]
	v_pk_fma_f32 v[186:187], v[34:35], v[138:139], v[186:187]
	v_pk_fma_f32 v[190:191], v[34:35], v[234:235], v[190:191]
	ds_read_b128 v[216:219], v237 offset:29440
	ds_read_b128 v[220:223], v237 offset:29456
	ds_read_b128 v[224:227], v237 offset:29472
	ds_read_b128 v[228:231], v237 offset:29488
	ds_read_b128 v[232:235], v237 offset:29504
	ds_read_b32 v184, v238 offset:1472
	v_add_f32_e32 v188, v186, v187
	v_pk_mul_f32 v[158:159], v[148:149], v[156:157] op_sel_hi:[1,0]
	v_add_f32_e32 v192, v190, v191
	v_add_f32_dpp v188, v188, v188 quad_perm:[1,0,3,2] row_mask:0xf bank_mask:0xf bound_ctrl:1
	v_pk_mul_f32 v[182:183], v[150:151], v[156:157] op_sel_hi:[1,0]
	v_add_f32_dpp v192, v192, v192 quad_perm:[1,0,3,2] row_mask:0xf bank_mask:0xf bound_ctrl:1
	v_add_f32_dpp v188, v188, v188 quad_perm:[2,3,0,1] row_mask:0xf bank_mask:0xf bound_ctrl:1
	v_pk_fma_f32 v[194:195], v[32:33], v[140:141], v[158:159]
	ds_write_b32 v193, v192 offset:10240
	v_add_f32_dpp v188, v188, v188 row_half_mirror row_mask:0xf bank_mask:0xf bound_ctrl:1
	v_pk_fma_f32 v[214:215], v[34:35], v[142:143], v[182:183]
	s_nop 0
	v_add_f32_dpp v188, v188, v188 row_mirror row_mask:0xf bank_mask:0xf bound_ctrl:1
	v_pk_fma_f32 v[32:33], v[144:145], v[188:189], v[194:195] op_sel_hi:[1,0,1]
	v_pk_fma_f32 v[34:35], v[146:147], v[188:189], v[214:215] op_sel_hi:[1,0,1]
	s_waitcnt lgkmcnt(8)
	v_pk_mul_f32 v[186:187], v[32:33], v[160:161]
	v_pk_mul_f32 v[190:191], v[32:33], v[152:153]
	v_pk_fma_f32 v[186:187], v[34:35], v[162:163], v[186:187]
	v_pk_fma_f32 v[190:191], v[34:35], v[154:155], v[190:191]
	ds_read_b128 v[136:139], v237 offset:30720
	ds_read_b128 v[140:143], v237 offset:30736
	ds_read_b128 v[144:147], v237 offset:30752
	ds_read_b128 v[148:151], v237 offset:30768
	ds_read_b128 v[152:155], v237 offset:30784
	ds_read_b32 v156, v238 offset:1536
	v_add_f32_e32 v188, v186, v187
	v_pk_mul_f32 v[158:159], v[172:173], v[180:181] op_sel_hi:[1,0]
	v_add_f32_e32 v192, v190, v191
	v_add_f32_dpp v188, v188, v188 quad_perm:[1,0,3,2] row_mask:0xf bank_mask:0xf bound_ctrl:1
	v_pk_mul_f32 v[182:183], v[174:175], v[180:181] op_sel_hi:[1,0]
	v_add_f32_dpp v192, v192, v192 quad_perm:[1,0,3,2] row_mask:0xf bank_mask:0xf bound_ctrl:1
	v_add_f32_dpp v188, v188, v188 quad_perm:[2,3,0,1] row_mask:0xf bank_mask:0xf bound_ctrl:1
	v_pk_fma_f32 v[194:195], v[32:33], v[164:165], v[158:159]
	ds_write_b32 v193, v192 offset:10752
	v_add_f32_dpp v188, v188, v188 row_half_mirror row_mask:0xf bank_mask:0xf bound_ctrl:1
	v_pk_fma_f32 v[214:215], v[34:35], v[166:167], v[182:183]
	s_nop 0
	v_add_f32_dpp v188, v188, v188 row_mirror row_mask:0xf bank_mask:0xf bound_ctrl:1
	v_pk_fma_f32 v[32:33], v[168:169], v[188:189], v[194:195] op_sel_hi:[1,0,1]
	v_pk_fma_f32 v[34:35], v[170:171], v[188:189], v[214:215] op_sel_hi:[1,0,1]
	s_waitcnt lgkmcnt(8)
	v_pk_mul_f32 v[186:187], v[32:33], v[216:217]
	v_pk_mul_f32 v[190:191], v[32:33], v[176:177]
	v_pk_fma_f32 v[186:187], v[34:35], v[218:219], v[186:187]
	v_pk_fma_f32 v[190:191], v[34:35], v[178:179], v[190:191]
	ds_read_b128 v[160:163], v237 offset:32000
	ds_read_b128 v[164:167], v237 offset:32016
	ds_read_b128 v[168:171], v237 offset:32032
	ds_read_b128 v[172:175], v237 offset:32048
	ds_read_b128 v[176:179], v237 offset:32064
	ds_read_b32 v180, v238 offset:1600
	v_add_f32_e32 v188, v186, v187
	v_pk_mul_f32 v[158:159], v[228:229], v[184:185] op_sel_hi:[1,0]
	v_add_f32_e32 v192, v190, v191
	v_add_f32_dpp v188, v188, v188 quad_perm:[1,0,3,2] row_mask:0xf bank_mask:0xf bound_ctrl:1
	v_pk_mul_f32 v[182:183], v[230:231], v[184:185] op_sel_hi:[1,0]
	v_add_f32_dpp v192, v192, v192 quad_perm:[1,0,3,2] row_mask:0xf bank_mask:0xf bound_ctrl:1
	v_add_f32_dpp v188, v188, v188 quad_perm:[2,3,0,1] row_mask:0xf bank_mask:0xf bound_ctrl:1
	v_pk_fma_f32 v[194:195], v[32:33], v[220:221], v[158:159]
	ds_write_b32 v193, v192 offset:11264
	v_add_f32_dpp v188, v188, v188 row_half_mirror row_mask:0xf bank_mask:0xf bound_ctrl:1
	v_pk_fma_f32 v[214:215], v[34:35], v[222:223], v[182:183]
	s_nop 0
	v_add_f32_dpp v188, v188, v188 row_mirror row_mask:0xf bank_mask:0xf bound_ctrl:1
	v_pk_fma_f32 v[32:33], v[224:225], v[188:189], v[194:195] op_sel_hi:[1,0,1]
	v_pk_fma_f32 v[34:35], v[226:227], v[188:189], v[214:215] op_sel_hi:[1,0,1]
	s_waitcnt lgkmcnt(8)
; DEVI void rwkv_scan_item(int TID_, int BID_, PREF p, int g, int item, char* shm) {
;     ...
;       for (int s = 0; s < TB; ++s) {
;         OpsR c = n1;
;         n1 = n2;
;         if (s + 2 < TB) n2 = ld(ob, vb, s + 2);
;         f2v a01 = {c.a.x, c.a.y}, a23 = {c.a.z, c.a.w}, w01 = {c.w.x, c.w.y}, w23 = {c.w.z, c.w.w},
;             b01 = {c.b.x, c.b.y}, b23 = {c.b.z, c.b.w}, k01 = {c.k.x, c.k.y}, k23 = {c.k.z, c.k.w},
;             r01 = {c.r.x, c.r.y}, r23 = {c.r.z, c.r.w};
;         f2v vv = {c.v, c.v};
;         f2v vk01 = vv * k01, vk23 = vv * k23;
;         f2v t = S01 * a01;
;         t = S23 * a23 + t;
;         float sa = allreduce16(t.x + t.y);
;         f2v sv = {sa, sa};
;         S01 = S01 * w01 + (sv * b01 + vk01);
;         S23 = S23 * w23 + (sv * b23 + vk23);
;         f2v u = S01 * r01;
;         u = S23 * r23 + u;
;         float uu = u.x + u.y;
;         uu += dppmov<0xB1>(uu);
;         yb[s * 128] = uu;
;       }
	v_pk_mul_f32 v[186:187], v[32:33], v[136:137]
	v_pk_mul_f32 v[190:191], v[32:33], v[232:233]
	v_pk_fma_f32 v[186:187], v[34:35], v[138:139], v[186:187]
	v_pk_fma_f32 v[190:191], v[34:35], v[234:235], v[190:191]
	ds_read_b128 v[216:219], v237 offset:33280
	ds_read_b128 v[220:223], v237 offset:33296
	ds_read_b128 v[224:227], v237 offset:33312
	ds_read_b128 v[228:231], v237 offset:33328
	ds_read_b128 v[232:235], v237 offset:33344
	ds_read_b32 v184, v238 offset:1664
	v_add_f32_e32 v188, v186, v187
	v_pk_mul_f32 v[158:159], v[148:149], v[156:157] op_sel_hi:[1,0]
	v_add_f32_e32 v192, v190, v191
	v_add_f32_dpp v188, v188, v188 quad_perm:[1,0,3,2] row_mask:0xf bank_mask:0xf bound_ctrl:1
	v_pk_mul_f32 v[182:183], v[150:151], v[156:157] op_sel_hi:[1,0]
	v_add_f32_dpp v192, v192, v192 quad_perm:[1,0,3,2] row_mask:0xf bank_mask:0xf bound_ctrl:1
	v_add_f32_dpp v188, v188, v188 quad_perm:[2,3,0,1] row_mask:0xf bank_mask:0xf bound_ctrl:1
	v_pk_fma_f32 v[194:195], v[32:33], v[140:141], v[158:159]
	ds_write_b32 v193, v192 offset:11776
	v_add_f32_dpp v188, v188, v188 row_half_mirror row_mask:0xf bank_mask:0xf bound_ctrl:1
	v_pk_fma_f32 v[214:215], v[34:35], v[142:143], v[182:183]
	s_nop 0
	v_add_f32_dpp v188, v188, v188 row_mirror row_mask:0xf bank_mask:0xf bound_ctrl:1
	v_pk_fma_f32 v[32:33], v[144:145], v[188:189], v[194:195] op_sel_hi:[1,0,1]
	v_pk_fma_f32 v[34:35], v[146:147], v[188:189], v[214:215] op_sel_hi:[1,0,1]
	s_waitcnt lgkmcnt(8)
	v_pk_mul_f32 v[186:187], v[32:33], v[160:161]
	v_pk_mul_f32 v[190:191], v[32:33], v[152:153]
	v_pk_fma_f32 v[186:187], v[34:35], v[162:163], v[186:187]
	v_pk_fma_f32 v[190:191], v[34:35], v[154:155], v[190:191]
	ds_read_b128 v[136:139], v237 offset:34560
	ds_read_b128 v[140:143], v237 offset:34576
	ds_read_b128 v[144:147], v237 offset:34592
	ds_read_b128 v[148:151], v237 offset:34608
	ds_read_b128 v[152:155], v237 offset:34624
	ds_read_b32 v156, v238 offset:1728
	v_add_f32_e32 v188, v186, v187
	v_pk_mul_f32 v[158:159], v[172:173], v[180:181] op_sel_hi:[1,0]
	v_add_f32_e32 v192, v190, v191
	v_add_f32_dpp v188, v188, v188 quad_perm:[1,0,3,2] row_mask:0xf bank_mask:0xf bound_ctrl:1
	v_pk_mul_f32 v[182:183], v[174:175], v[180:181] op_sel_hi:[1,0]
	v_add_f32_dpp v192, v192, v192 quad_perm:[1,0,3,2] row_mask:0xf bank_mask:0xf bound_ctrl:1
	v_add_f32_dpp v188, v188, v188 quad_perm:[2,3,0,1] row_mask:0xf bank_mask:0xf bound_ctrl:1
	v_pk_fma_f32 v[194:195], v[32:33], v[164:165], v[158:159]
	ds_write_b32 v193, v192 offset:12288
	v_add_f32_dpp v188, v188, v188 row_half_mirror row_mask:0xf bank_mask:0xf bound_ctrl:1
	v_pk_fma_f32 v[214:215], v[34:35], v[166:167], v[182:183]
	s_nop 0
	v_add_f32_dpp v188, v188, v188 row_mirror row_mask:0xf bank_mask:0xf bound_ctrl:1
	v_pk_fma_f32 v[32:33], v[168:169], v[188:189], v[194:195] op_sel_hi:[1,0,1]
	v_pk_fma_f32 v[34:35], v[170:171], v[188:189], v[214:215] op_sel_hi:[1,0,1]
	s_waitcnt lgkmcnt(8)
	v_pk_mul_f32 v[186:187], v[32:33], v[216:217]
	v_pk_mul_f32 v[190:191], v[32:33], v[176:177]
	v_pk_fma_f32 v[186:187], v[34:35], v[218:219], v[186:187]
	v_pk_fma_f32 v[190:191], v[34:35], v[178:179], v[190:191]
	ds_read_b128 v[160:163], v237 offset:35840
	ds_read_b128 v[164:167], v237 offset:35856
	ds_read_b128 v[168:171], v237 offset:35872
	ds_read_b128 v[172:175], v237 offset:35888
	ds_read_b128 v[176:179], v237 offset:35904
	ds_read_b32 v180, v238 offset:1792
	v_add_f32_e32 v188, v186, v187
	v_pk_mul_f32 v[158:159], v[228:229], v[184:185] op_sel_hi:[1,0]
	v_add_f32_e32 v192, v190, v191
	v_add_f32_dpp v188, v188, v188 quad_perm:[1,0,3,2] row_mask:0xf bank_mask:0xf bound_ctrl:1
	v_pk_mul_f32 v[182:183], v[230:231], v[184:185] op_sel_hi:[1,0]
	v_add_f32_dpp v192, v192, v192 quad_perm:[1,0,3,2] row_mask:0xf bank_mask:0xf bound_ctrl:1
	v_add_f32_dpp v188, v188, v188 quad_perm:[2,3,0,1] row_mask:0xf bank_mask:0xf bound_ctrl:1
	v_pk_fma_f32 v[194:195], v[32:33], v[220:221], v[158:159]
	ds_write_b32 v193, v192 offset:12800
	v_add_f32_dpp v188, v188, v188 row_half_mirror row_mask:0xf bank_mask:0xf bound_ctrl:1
	v_pk_fma_f32 v[214:215], v[34:35], v[222:223], v[182:183]
	s_nop 0
	v_add_f32_dpp v188, v188, v188 row_mirror row_mask:0xf bank_mask:0xf bound_ctrl:1
	v_pk_fma_f32 v[32:33], v[224:225], v[188:189], v[194:195] op_sel_hi:[1,0,1]
	v_pk_fma_f32 v[34:35], v[226:227], v[188:189], v[214:215] op_sel_hi:[1,0,1]
	s_waitcnt lgkmcnt(8)
	v_pk_mul_f32 v[186:187], v[32:33], v[136:137]
	v_pk_mul_f32 v[190:191], v[32:33], v[232:233]
	v_pk_fma_f32 v[186:187], v[34:35], v[138:139], v[186:187]
	v_pk_fma_f32 v[190:191], v[34:35], v[234:235], v[190:191]
	ds_read_b128 v[216:219], v237 offset:37120
	ds_read_b128 v[220:223], v237 offset:37136
	ds_read_b128 v[224:227], v237 offset:37152
	ds_read_b128 v[228:231], v237 offset:37168
	ds_read_b128 v[232:235], v237 offset:37184
	ds_read_b32 v184, v238 offset:1856
	v_add_f32_e32 v188, v186, v187
	v_pk_mul_f32 v[158:159], v[148:149], v[156:157] op_sel_hi:[1,0]
	v_add_f32_e32 v192, v190, v191
	v_add_f32_dpp v188, v188, v188 quad_perm:[1,0,3,2] row_mask:0xf bank_mask:0xf bound_ctrl:1
	v_pk_mul_f32 v[182:183], v[150:151], v[156:157] op_sel_hi:[1,0]
	v_add_f32_dpp v192, v192, v192 quad_perm:[1,0,3,2] row_mask:0xf bank_mask:0xf bound_ctrl:1
	v_add_f32_dpp v188, v188, v188 quad_perm:[2,3,0,1] row_mask:0xf bank_mask:0xf bound_ctrl:1
	v_pk_fma_f32 v[194:195], v[32:33], v[140:141], v[158:159]
	ds_write_b32 v193, v192 offset:13312
	v_add_f32_dpp v188, v188, v188 row_half_mirror row_mask:0xf bank_mask:0xf bound_ctrl:1
	v_pk_fma_f32 v[214:215], v[34:35], v[142:143], v[182:183]
	s_nop 0
	v_add_f32_dpp v188, v188, v188 row_mirror row_mask:0xf bank_mask:0xf bound_ctrl:1
	v_pk_fma_f32 v[32:33], v[144:145], v[188:189], v[194:195] op_sel_hi:[1,0,1]
	v_pk_fma_f32 v[34:35], v[146:147], v[188:189], v[214:215] op_sel_hi:[1,0,1]
	s_waitcnt lgkmcnt(8)
; DEVI void rwkv_scan_item(int TID_, int BID_, PREF p, int g, int item, char* shm) {
;     ...
;       for (int s = 0; s < TB; ++s) {
;         OpsR c = n1;
;         n1 = n2;
;         if (s + 2 < TB) n2 = ld(ob, vb, s + 2);
;         f2v a01 = {c.a.x, c.a.y}, a23 = {c.a.z, c.a.w}, w01 = {c.w.x, c.w.y}, w23 = {c.w.z, c.w.w},
;             b01 = {c.b.x, c.b.y}, b23 = {c.b.z, c.b.w}, k01 = {c.k.x, c.k.y}, k23 = {c.k.z, c.k.w},
;             r01 = {c.r.x, c.r.y}, r23 = {c.r.z, c.r.w};
;         f2v vv = {c.v, c.v};
;         f2v vk01 = vv * k01, vk23 = vv * k23;
;         f2v t = S01 * a01;
;         t = S23 * a23 + t;
;         float sa = allreduce16(t.x + t.y);
;         f2v sv = {sa, sa};
;         S01 = S01 * w01 + (sv * b01 + vk01);
;         S23 = S23 * w23 + (sv * b23 + vk23);
;         f2v u = S01 * r01;
;         u = S23 * r23 + u;
;         float uu = u.x + u.y;
;         uu += dppmov<0xB1>(uu);
;         yb[s * 128] = uu;
;       }
;     }
	v_pk_mul_f32 v[186:187], v[32:33], v[160:161]
	v_pk_mul_f32 v[190:191], v[32:33], v[152:153]
	v_pk_fma_f32 v[186:187], v[34:35], v[162:163], v[186:187]
	v_pk_fma_f32 v[190:191], v[34:35], v[154:155], v[190:191]
	ds_read_b128 v[136:139], v237 offset:38400
	ds_read_b128 v[140:143], v237 offset:38416
	ds_read_b128 v[144:147], v237 offset:38432
	ds_read_b128 v[148:151], v237 offset:38448
	ds_read_b128 v[152:155], v237 offset:38464
	ds_read_b32 v156, v238 offset:1920
	v_add_f32_e32 v188, v186, v187
	v_pk_mul_f32 v[158:159], v[172:173], v[180:181] op_sel_hi:[1,0]
	v_add_f32_e32 v192, v190, v191
	v_add_f32_dpp v188, v188, v188 quad_perm:[1,0,3,2] row_mask:0xf bank_mask:0xf bound_ctrl:1
	v_pk_mul_f32 v[182:183], v[174:175], v[180:181] op_sel_hi:[1,0]
	v_add_f32_dpp v192, v192, v192 quad_perm:[1,0,3,2] row_mask:0xf bank_mask:0xf bound_ctrl:1
	v_add_f32_dpp v188, v188, v188 quad_perm:[2,3,0,1] row_mask:0xf bank_mask:0xf bound_ctrl:1
	v_pk_fma_f32 v[194:195], v[32:33], v[164:165], v[158:159]
	ds_write_b32 v193, v192 offset:13824
	v_add_f32_dpp v188, v188, v188 row_half_mirror row_mask:0xf bank_mask:0xf bound_ctrl:1
	v_pk_fma_f32 v[214:215], v[34:35], v[166:167], v[182:183]
	s_nop 0
	v_add_f32_dpp v188, v188, v188 row_mirror row_mask:0xf bank_mask:0xf bound_ctrl:1
	v_pk_fma_f32 v[32:33], v[168:169], v[188:189], v[194:195] op_sel_hi:[1,0,1]
	v_pk_fma_f32 v[34:35], v[170:171], v[188:189], v[214:215] op_sel_hi:[1,0,1]
	s_waitcnt lgkmcnt(8)
	v_pk_mul_f32 v[186:187], v[32:33], v[216:217]
	v_pk_mul_f32 v[190:191], v[32:33], v[176:177]
	v_pk_fma_f32 v[186:187], v[34:35], v[218:219], v[186:187]
	v_pk_fma_f32 v[190:191], v[34:35], v[178:179], v[190:191]
	ds_read_b128 v[160:163], v237 offset:39680
	ds_read_b128 v[164:167], v237 offset:39696
	ds_read_b128 v[168:171], v237 offset:39712
	ds_read_b128 v[172:175], v237 offset:39728
	ds_read_b128 v[176:179], v237 offset:39744
	ds_read_b32 v180, v238 offset:1984
	v_add_f32_e32 v188, v186, v187
	v_pk_mul_f32 v[158:159], v[228:229], v[184:185] op_sel_hi:[1,0]
	v_add_f32_e32 v192, v190, v191
	v_add_f32_dpp v188, v188, v188 quad_perm:[1,0,3,2] row_mask:0xf bank_mask:0xf bound_ctrl:1
	v_pk_mul_f32 v[182:183], v[230:231], v[184:185] op_sel_hi:[1,0]
	v_add_f32_dpp v192, v192, v192 quad_perm:[1,0,3,2] row_mask:0xf bank_mask:0xf bound_ctrl:1
	v_add_f32_dpp v188, v188, v188 quad_perm:[2,3,0,1] row_mask:0xf bank_mask:0xf bound_ctrl:1
	v_pk_fma_f32 v[194:195], v[32:33], v[220:221], v[158:159]
	ds_write_b32 v193, v192 offset:14336
	v_add_f32_dpp v188, v188, v188 row_half_mirror row_mask:0xf bank_mask:0xf bound_ctrl:1
	v_pk_fma_f32 v[214:215], v[34:35], v[222:223], v[182:183]
	s_nop 0
	v_add_f32_dpp v188, v188, v188 row_mirror row_mask:0xf bank_mask:0xf bound_ctrl:1
	v_pk_fma_f32 v[32:33], v[224:225], v[188:189], v[194:195] op_sel_hi:[1,0,1]
	v_pk_fma_f32 v[34:35], v[226:227], v[188:189], v[214:215] op_sel_hi:[1,0,1]
	s_waitcnt lgkmcnt(8)
	v_pk_mul_f32 v[186:187], v[32:33], v[136:137]
	v_pk_mul_f32 v[190:191], v[32:33], v[232:233]
	v_pk_fma_f32 v[186:187], v[34:35], v[138:139], v[186:187]
	v_pk_fma_f32 v[190:191], v[34:35], v[234:235], v[190:191]
	v_add_f32_e32 v188, v186, v187
	v_pk_mul_f32 v[158:159], v[148:149], v[156:157] op_sel_hi:[1,0]
	v_add_f32_e32 v192, v190, v191
	v_add_f32_dpp v188, v188, v188 quad_perm:[1,0,3,2] row_mask:0xf bank_mask:0xf bound_ctrl:1
	v_pk_mul_f32 v[182:183], v[150:151], v[156:157] op_sel_hi:[1,0]
	v_add_f32_dpp v192, v192, v192 quad_perm:[1,0,3,2] row_mask:0xf bank_mask:0xf bound_ctrl:1
	v_add_f32_dpp v188, v188, v188 quad_perm:[2,3,0,1] row_mask:0xf bank_mask:0xf bound_ctrl:1
	v_pk_fma_f32 v[194:195], v[32:33], v[140:141], v[158:159]
	ds_write_b32 v193, v192 offset:14848
	v_add_f32_dpp v188, v188, v188 row_half_mirror row_mask:0xf bank_mask:0xf bound_ctrl:1
	v_pk_fma_f32 v[214:215], v[34:35], v[142:143], v[182:183]
	s_nop 0
	v_add_f32_dpp v188, v188, v188 row_mirror row_mask:0xf bank_mask:0xf bound_ctrl:1
	v_pk_fma_f32 v[32:33], v[144:145], v[188:189], v[194:195] op_sel_hi:[1,0,1]
	v_pk_fma_f32 v[34:35], v[146:147], v[188:189], v[214:215] op_sel_hi:[1,0,1]
	s_waitcnt lgkmcnt(2)
	v_pk_mul_f32 v[186:187], v[32:33], v[160:161]
	v_pk_mul_f32 v[190:191], v[32:33], v[152:153]
	v_pk_fma_f32 v[186:187], v[34:35], v[162:163], v[186:187]
	v_pk_fma_f32 v[190:191], v[34:35], v[154:155], v[190:191]
	v_add_f32_e32 v188, v186, v187
	v_pk_mul_f32 v[158:159], v[172:173], v[180:181] op_sel_hi:[1,0]
	v_add_f32_e32 v192, v190, v191
	v_add_f32_dpp v188, v188, v188 quad_perm:[1,0,3,2] row_mask:0xf bank_mask:0xf bound_ctrl:1
	v_pk_mul_f32 v[182:183], v[174:175], v[180:181] op_sel_hi:[1,0]
	v_add_f32_dpp v192, v192, v192 quad_perm:[1,0,3,2] row_mask:0xf bank_mask:0xf bound_ctrl:1
	v_add_f32_dpp v188, v188, v188 quad_perm:[2,3,0,1] row_mask:0xf bank_mask:0xf bound_ctrl:1
	v_pk_fma_f32 v[194:195], v[32:33], v[164:165], v[158:159]
	ds_write_b32 v193, v192 offset:15360
	v_add_f32_dpp v188, v188, v188 row_half_mirror row_mask:0xf bank_mask:0xf bound_ctrl:1
	v_pk_fma_f32 v[214:215], v[34:35], v[166:167], v[182:183]
	s_nop 0
	v_add_f32_dpp v188, v188, v188 row_mirror row_mask:0xf bank_mask:0xf bound_ctrl:1
	v_pk_fma_f32 v[32:33], v[168:169], v[188:189], v[194:195] op_sel_hi:[1,0,1]
	v_pk_fma_f32 v[34:35], v[170:171], v[188:189], v[214:215] op_sel_hi:[1,0,1]
	v_pk_mul_f32 v[190:191], v[32:33], v[176:177]
	v_pk_fma_f32 v[190:191], v[34:35], v[178:179], v[190:191]
	v_add_f32_e32 v192, v190, v191
	v_add_u32_e32 v45, 1, v43
	s_nop 0
	v_add_f32_dpp v192, v192, v192 quad_perm:[1,0,3,2] row_mask:0xf bank_mask:0xf bound_ctrl:1
	ds_write_b32 v193, v192 offset:15872

; DEVI void rwkv_scan_item(int TID_, int BID_, PREF p, int g, int item, char* shm) {
;     ...
;     const int buf = tb & 1;
;     if (wave >= 4) {
;       if (tb + 1 < nblk) commit_block(buf ^ 1);
;       if (tb + 2 < nblk) issue_block(tb + 2);
;       if (tb > 0) flush_block(tb - 1, buf ^ 1);
;     } else {
;       const float* ob = opbuf + ((size_t)buf * TB * 16 + jg) * 20;
;       const float* vb = vbuf + buf * TB * 16 + row;
;       float* yb = ybuf + ((size_t)buf * TB * 16 + row) * 8 + (jg >> 1);
;       OpsR n1 = ld(ob, vb, 0), n2 = ld(ob, vb, 1);
; #pragma unroll
;       for (int s = 0; s < TB; ++s) {
;         OpsR c = n1;
;         n1 = n2;
;         if (s + 2 < TB) n2 = ld(ob, vb, s + 2);
;         f2v a01 = {c.a.x, c.a.y}, a23 = {c.a.z, c.a.w}, w01 = {c.w.x, c.w.y}, w23 = {c.w.z, c.w.w},
;             b01 = {c.b.x, c.b.y}, b23 = {c.b.z, c.b.w}, k01 = {c.k.x, c.k.y}, k23 = {c.k.z, c.k.w},
;             r01 = {c.r.x, c.r.y}, r23 = {c.r.z, c.r.w};
;         f2v vv = {c.v, c.v};
;         f2v vk01 = vv * k01, vk23 = vv * k23;
;         f2v t = S01 * a01;
;         t = S23 * a23 + t;
;         float sa = allreduce16(t.x + t.y);
;         f2v sv = {sa, sa};
;         S01 = S01 * w01 + (sv * b01 + vk01);
;         S23 = S23 * w23 + (sv * b23 + vk23);
;         f2v u = S01 * r01;
;         u = S23 * r23 + u;
;         float uu = u.x + u.y;
;         uu += dppmov<0xB1>(uu);
;         yb[s * 128] = uu;
;       }
.LBB0_239:
	v_and_b32_e32 v40, 1, v38
	s_and_saveexec_b64 s[24:25], s[6:7]
	s_xor_b64 s[24:25], exec, s[24:25]
	s_cbranch_execz .LBB0_241
	v_lshlrev_b32_e32 v186, 9, v40
	v_or_b32_e32 v237, v186, v22
	v_mul_u32_u24_e32 v237, 0x50, v237
	v_lshl_add_u32 v238, v40, 11, v59
	v_add_u32_e32 v193, v186, v46
	v_lshl_add_u32 v193, v193, 5, v60
	ds_read_b128 v[136:139], v237
	ds_read_b128 v[140:143], v237 offset:16
	ds_read_b128 v[144:147], v237 offset:32
	ds_read_b128 v[148:151], v237 offset:48
	ds_read_b128 v[152:155], v237 offset:64
	ds_read_b32 v156, v238
	ds_read_b128 v[160:163], v237 offset:1280
	ds_read_b128 v[164:167], v237 offset:1296
	ds_read_b128 v[168:171], v237 offset:1312
	ds_read_b128 v[172:175], v237 offset:1328
	ds_read_b128 v[176:179], v237 offset:1344
	ds_read_b32 v180, v238 offset:64
	s_waitcnt lgkmcnt(6)
	v_pk_mul_f32 v[186:187], v[32:33], v[136:137]
	v_pk_fma_f32 v[186:187], v[34:35], v[138:139], v[186:187]
	ds_read_b128 v[216:219], v237 offset:2560
	ds_read_b128 v[220:223], v237 offset:2576
	ds_read_b128 v[224:227], v237 offset:2592
	ds_read_b128 v[228:231], v237 offset:2608
	ds_read_b128 v[232:235], v237 offset:2624
	ds_read_b32 v184, v238 offset:128
	v_add_f32_e32 v188, v186, v187
	v_pk_mul_f32 v[158:159], v[148:149], v[156:157] op_sel_hi:[1,0]
	s_nop 0
	v_add_f32_dpp v188, v188, v188 quad_perm:[1,0,3,2] row_mask:0xf bank_mask:0xf bound_ctrl:1
	v_pk_mul_f32 v[182:183], v[150:151], v[156:157] op_sel_hi:[1,0]
	s_nop 0
	v_add_f32_dpp v188, v188, v188 quad_perm:[2,3,0,1] row_mask:0xf bank_mask:0xf bound_ctrl:1
	v_pk_fma_f32 v[194:195], v[32:33], v[140:141], v[158:159]
	s_nop 0
	v_add_f32_dpp v188, v188, v188 row_half_mirror row_mask:0xf bank_mask:0xf bound_ctrl:1
	v_pk_fma_f32 v[214:215], v[34:35], v[142:143], v[182:183]
	s_nop 0
	v_add_f32_dpp v188, v188, v188 row_mirror row_mask:0xf bank_mask:0xf bound_ctrl:1
	v_pk_fma_f32 v[32:33], v[144:145], v[188:189], v[194:195] op_sel_hi:[1,0,1]
	v_pk_fma_f32 v[34:35], v[146:147], v[188:189], v[214:215] op_sel_hi:[1,0,1]
	s_waitcnt lgkmcnt(6)
	v_pk_mul_f32 v[186:187], v[32:33], v[160:161]
	v_pk_mul_f32 v[190:191], v[32:33], v[152:153]
	v_pk_fma_f32 v[186:187], v[34:35], v[162:163], v[186:187]
	v_pk_fma_f32 v[190:191], v[34:35], v[154:155], v[190:191]
	ds_read_b128 v[136:139], v237 offset:3840
	ds_read_b128 v[140:143], v237 offset:3856
	ds_read_b128 v[144:147], v237 offset:3872
	ds_read_b128 v[148:151], v237 offset:3888
	ds_read_b128 v[152:155], v237 offset:3904
	ds_read_b32 v156, v238 offset:192
	v_add_f32_e32 v188, v186, v187
	v_pk_mul_f32 v[158:159], v[172:173], v[180:181] op_sel_hi:[1,0]
	v_add_f32_e32 v192, v190, v191
	v_add_f32_dpp v188, v188, v188 quad_perm:[1,0,3,2] row_mask:0xf bank_mask:0xf bound_ctrl:1
	v_pk_mul_f32 v[182:183], v[174:175], v[180:181] op_sel_hi:[1,0]
	v_add_f32_dpp v192, v192, v192 quad_perm:[1,0,3,2] row_mask:0xf bank_mask:0xf bound_ctrl:1
	v_add_f32_dpp v188, v188, v188 quad_perm:[2,3,0,1] row_mask:0xf bank_mask:0xf bound_ctrl:1
	v_pk_fma_f32 v[194:195], v[32:33], v[164:165], v[158:159]
	ds_write_b32 v193, v192
	v_add_f32_dpp v188, v188, v188 row_half_mirror row_mask:0xf bank_mask:0xf bound_ctrl:1
	v_pk_fma_f32 v[214:215], v[34:35], v[166:167], v[182:183]
	s_nop 0
	v_add_f32_dpp v188, v188, v188 row_mirror row_mask:0xf bank_mask:0xf bound_ctrl:1
	v_pk_fma_f32 v[32:33], v[168:169], v[188:189], v[194:195] op_sel_hi:[1,0,1]
	v_pk_fma_f32 v[34:35], v[170:171], v[188:189], v[214:215] op_sel_hi:[1,0,1]
	s_waitcnt lgkmcnt(7)
	v_pk_mul_f32 v[186:187], v[32:33], v[216:217]
	v_pk_mul_f32 v[190:191], v[32:33], v[176:177]
	v_pk_fma_f32 v[186:187], v[34:35], v[218:219], v[186:187]
	v_pk_fma_f32 v[190:191], v[34:35], v[178:179], v[190:191]
	ds_read_b128 v[160:163], v237 offset:5120
	ds_read_b128 v[164:167], v237 offset:5136
	ds_read_b128 v[168:171], v237 offset:5152
	ds_read_b128 v[172:175], v237 offset:5168
	ds_read_b128 v[176:179], v237 offset:5184
	ds_read_b32 v180, v238 offset:256
	v_add_f32_e32 v188, v186, v187
	v_pk_mul_f32 v[158:159], v[228:229], v[184:185] op_sel_hi:[1,0]
	v_add_f32_e32 v192, v190, v191
	v_add_f32_dpp v188, v188, v188 quad_perm:[1,0,3,2] row_mask:0xf bank_mask:0xf bound_ctrl:1
	v_pk_mul_f32 v[182:183], v[230:231], v[184:185] op_sel_hi:[1,0]
	v_add_f32_dpp v192, v192, v192 quad_perm:[1,0,3,2] row_mask:0xf bank_mask:0xf bound_ctrl:1
	v_add_f32_dpp v188, v188, v188 quad_perm:[2,3,0,1] row_mask:0xf bank_mask:0xf bound_ctrl:1
	v_pk_fma_f32 v[194:195], v[32:33], v[220:221], v[158:159]
	ds_write_b32 v193, v192 offset:512
	v_add_f32_dpp v188, v188, v188 row_half_mirror row_mask:0xf bank_mask:0xf bound_ctrl:1
	v_pk_fma_f32 v[214:215], v[34:35], v[222:223], v[182:183]
	s_nop 0
	v_add_f32_dpp v188, v188, v188 row_mirror row_mask:0xf bank_mask:0xf bound_ctrl:1
	v_pk_fma_f32 v[32:33], v[224:225], v[188:189], v[194:195] op_sel_hi:[1,0,1]
	v_pk_fma_f32 v[34:35], v[226:227], v[188:189], v[214:215] op_sel_hi:[1,0,1]
	s_waitcnt lgkmcnt(8)
	v_pk_mul_f32 v[186:187], v[32:33], v[136:137]
	v_pk_mul_f32 v[190:191], v[32:33], v[232:233]
	v_pk_fma_f32 v[186:187], v[34:35], v[138:139], v[186:187]
	v_pk_fma_f32 v[190:191], v[34:35], v[234:235], v[190:191]
	ds_read_b128 v[216:219], v237 offset:6400
	ds_read_b128 v[220:223], v237 offset:6416
	ds_read_b128 v[224:227], v237 offset:6432
	ds_read_b128 v[228:231], v237 offset:6448
	ds_read_b128 v[232:235], v237 offset:6464
	ds_read_b32 v184, v238 offset:320
	v_add_f32_e32 v188, v186, v187
	v_pk_mul_f32 v[158:159], v[148:149], v[156:157] op_sel_hi:[1,0]
	v_add_f32_e32 v192, v190, v191
	v_add_f32_dpp v188, v188, v188 quad_perm:[1,0,3,2] row_mask:0xf bank_mask:0xf bound_ctrl:1
	v_pk_mul_f32 v[182:183], v[150:151], v[156:157] op_sel_hi:[1,0]
	v_add_f32_dpp v192, v192, v192 quad_perm:[1,0,3,2] row_mask:0xf bank_mask:0xf bound_ctrl:1
	v_add_f32_dpp v188, v188, v188 quad_perm:[2,3,0,1] row_mask:0xf bank_mask:0xf bound_ctrl:1
	v_pk_fma_f32 v[194:195], v[32:33], v[140:141], v[158:159]
	ds_write_b32 v193, v192 offset:1024
	v_add_f32_dpp v188, v188, v188 row_half_mirror row_mask:0xf bank_mask:0xf bound_ctrl:1
	v_pk_fma_f32 v[214:215], v[34:35], v[142:143], v[182:183]
	s_nop 0
	v_add_f32_dpp v188, v188, v188 row_mirror row_mask:0xf bank_mask:0xf bound_ctrl:1
	v_pk_fma_f32 v[32:33], v[144:145], v[188:189], v[194:195] op_sel_hi:[1,0,1]
	v_pk_fma_f32 v[34:35], v[146:147], v[188:189], v[214:215] op_sel_hi:[1,0,1]
	s_waitcnt lgkmcnt(8)
; DEVI void rwkv_scan_item(int TID_, int BID_, PREF p, int g, int item, char* shm) {
;     ...
;       for (int s = 0; s < TB; ++s) {
;         OpsR c = n1;
;         n1 = n2;
;         if (s + 2 < TB) n2 = ld(ob, vb, s + 2);
;         f2v a01 = {c.a.x, c.a.y}, a23 = {c.a.z, c.a.w}, w01 = {c.w.x, c.w.y}, w23 = {c.w.z, c.w.w},
;             b01 = {c.b.x, c.b.y}, b23 = {c.b.z, c.b.w}, k01 = {c.k.x, c.k.y}, k23 = {c.k.z, c.k.w},
;             r01 = {c.r.x, c.r.y}, r23 = {c.r.z, c.r.w};
;         f2v vv = {c.v, c.v};
;         f2v vk01 = vv * k01, vk23 = vv * k23;
;         f2v t = S01 * a01;
;         t = S23 * a23 + t;
;         float sa = allreduce16(t.x + t.y);
;         f2v sv = {sa, sa};
;         S01 = S01 * w01 + (sv * b01 + vk01);
;         S23 = S23 * w23 + (sv * b23 + vk23);
;         f2v u = S01 * r01;
;         u = S23 * r23 + u;
;         float uu = u.x + u.y;
;         uu += dppmov<0xB1>(uu);
;         yb[s * 128] = uu;
;       }
	v_pk_mul_f32 v[186:187], v[32:33], v[160:161]
	v_pk_mul_f32 v[190:191], v[32:33], v[152:153]
	v_pk_fma_f32 v[186:187], v[34:35], v[162:163], v[186:187]
	v_pk_fma_f32 v[190:191], v[34:35], v[154:155], v[190:191]
	ds_read_b128 v[136:139], v237 offset:7680
	ds_read_b128 v[140:143], v237 offset:7696
	ds_read_b128 v[144:147], v237 offset:7712
	ds_read_b128 v[148:151], v237 offset:7728
	ds_read_b128 v[152:155], v237 offset:7744
	ds_read_b32 v156, v238 offset:384
	v_add_f32_e32 v188, v186, v187
	v_pk_mul_f32 v[158:159], v[172:173], v[180:181] op_sel_hi:[1,0]
	v_add_f32_e32 v192, v190, v191
	v_add_f32_dpp v188, v188, v188 quad_perm:[1,0,3,2] row_mask:0xf bank_mask:0xf bound_ctrl:1
	v_pk_mul_f32 v[182:183], v[174:175], v[180:181] op_sel_hi:[1,0]
	v_add_f32_dpp v192, v192, v192 quad_perm:[1,0,3,2] row_mask:0xf bank_mask:0xf bound_ctrl:1
	v_add_f32_dpp v188, v188, v188 quad_perm:[2,3,0,1] row_mask:0xf bank_mask:0xf bound_ctrl:1
	v_pk_fma_f32 v[194:195], v[32:33], v[164:165], v[158:159]
	ds_write_b32 v193, v192 offset:1536
	v_add_f32_dpp v188, v188, v188 row_half_mirror row_mask:0xf bank_mask:0xf bound_ctrl:1
	v_pk_fma_f32 v[214:215], v[34:35], v[166:167], v[182:183]
	s_nop 0
	v_add_f32_dpp v188, v188, v188 row_mirror row_mask:0xf bank_mask:0xf bound_ctrl:1
	v_pk_fma_f32 v[32:33], v[168:169], v[188:189], v[194:195] op_sel_hi:[1,0,1]
	v_pk_fma_f32 v[34:35], v[170:171], v[188:189], v[214:215] op_sel_hi:[1,0,1]
	s_waitcnt lgkmcnt(8)
	v_pk_mul_f32 v[186:187], v[32:33], v[216:217]
	v_pk_mul_f32 v[190:191], v[32:33], v[176:177]
	v_pk_fma_f32 v[186:187], v[34:35], v[218:219], v[186:187]
	v_pk_fma_f32 v[190:191], v[34:35], v[178:179], v[190:191]
	ds_read_b128 v[160:163], v237 offset:8960
	ds_read_b128 v[164:167], v237 offset:8976
	ds_read_b128 v[168:171], v237 offset:8992
	ds_read_b128 v[172:175], v237 offset:9008
	ds_read_b128 v[176:179], v237 offset:9024
	ds_read_b32 v180, v238 offset:448
	v_add_f32_e32 v188, v186, v187
	v_pk_mul_f32 v[158:159], v[228:229], v[184:185] op_sel_hi:[1,0]
	v_add_f32_e32 v192, v190, v191
	v_add_f32_dpp v188, v188, v188 quad_perm:[1,0,3,2] row_mask:0xf bank_mask:0xf bound_ctrl:1
	v_pk_mul_f32 v[182:183], v[230:231], v[184:185] op_sel_hi:[1,0]
	v_add_f32_dpp v192, v192, v192 quad_perm:[1,0,3,2] row_mask:0xf bank_mask:0xf bound_ctrl:1
	v_add_f32_dpp v188, v188, v188 quad_perm:[2,3,0,1] row_mask:0xf bank_mask:0xf bound_ctrl:1
	v_pk_fma_f32 v[194:195], v[32:33], v[220:221], v[158:159]
	ds_write_b32 v193, v192 offset:2048
	v_add_f32_dpp v188, v188, v188 row_half_mirror row_mask:0xf bank_mask:0xf bound_ctrl:1
	v_pk_fma_f32 v[214:215], v[34:35], v[222:223], v[182:183]
	s_nop 0
	v_add_f32_dpp v188, v188, v188 row_mirror row_mask:0xf bank_mask:0xf bound_ctrl:1
	v_pk_fma_f32 v[32:33], v[224:225], v[188:189], v[194:195] op_sel_hi:[1,0,1]
	v_pk_fma_f32 v[34:35], v[226:227], v[188:189], v[214:215] op_sel_hi:[1,0,1]
	s_waitcnt lgkmcnt(8)
	v_pk_mul_f32 v[186:187], v[32:33], v[136:137]
	v_pk_mul_f32 v[190:191], v[32:33], v[232:233]
	v_pk_fma_f32 v[186:187], v[34:35], v[138:139], v[186:187]
	v_pk_fma_f32 v[190:191], v[34:35], v[234:235], v[190:191]
	ds_read_b128 v[216:219], v237 offset:10240
	ds_read_b128 v[220:223], v237 offset:10256
	ds_read_b128 v[224:227], v237 offset:10272
	ds_read_b128 v[228:231], v237 offset:10288
	ds_read_b128 v[232:235], v237 offset:10304
	ds_read_b32 v184, v238 offset:512
	v_add_f32_e32 v188, v186, v187
	v_pk_mul_f32 v[158:159], v[148:149], v[156:157] op_sel_hi:[1,0]
	v_add_f32_e32 v192, v190, v191
	v_add_f32_dpp v188, v188, v188 quad_perm:[1,0,3,2] row_mask:0xf bank_mask:0xf bound_ctrl:1
	v_pk_mul_f32 v[182:183], v[150:151], v[156:157] op_sel_hi:[1,0]
	v_add_f32_dpp v192, v192, v192 quad_perm:[1,0,3,2] row_mask:0xf bank_mask:0xf bound_ctrl:1
	v_add_f32_dpp v188, v188, v188 quad_perm:[2,3,0,1] row_mask:0xf bank_mask:0xf bound_ctrl:1
	v_pk_fma_f32 v[194:195], v[32:33], v[140:141], v[158:159]
	ds_write_b32 v193, v192 offset:2560
	v_add_f32_dpp v188, v188, v188 row_half_mirror row_mask:0xf bank_mask:0xf bound_ctrl:1
	v_pk_fma_f32 v[214:215], v[34:35], v[142:143], v[182:183]
	s_nop 0
	v_add_f32_dpp v188, v188, v188 row_mirror row_mask:0xf bank_mask:0xf bound_ctrl:1
	v_pk_fma_f32 v[32:33], v[144:145], v[188:189], v[194:195] op_sel_hi:[1,0,1]
	v_pk_fma_f32 v[34:35], v[146:147], v[188:189], v[214:215] op_sel_hi:[1,0,1]
	s_waitcnt lgkmcnt(8)
	v_pk_mul_f32 v[186:187], v[32:33], v[160:161]
	v_pk_mul_f32 v[190:191], v[32:33], v[152:153]
	v_pk_fma_f32 v[186:187], v[34:35], v[162:163], v[186:187]
	v_pk_fma_f32 v[190:191], v[34:35], v[154:155], v[190:191]
	ds_read_b128 v[136:139], v237 offset:11520
	ds_read_b128 v[140:143], v237 offset:11536
	ds_read_b128 v[144:147], v237 offset:11552
	ds_read_b128 v[148:151], v237 offset:11568
	ds_read_b128 v[152:155], v237 offset:11584
	ds_read_b32 v156, v238 offset:576
	v_add_f32_e32 v188, v186, v187
	v_pk_mul_f32 v[158:159], v[172:173], v[180:181] op_sel_hi:[1,0]
	v_add_f32_e32 v192, v190, v191
	v_add_f32_dpp v188, v188, v188 quad_perm:[1,0,3,2] row_mask:0xf bank_mask:0xf bound_ctrl:1
	v_pk_mul_f32 v[182:183], v[174:175], v[180:181] op_sel_hi:[1,0]
	v_add_f32_dpp v192, v192, v192 quad_perm:[1,0,3,2] row_mask:0xf bank_mask:0xf bound_ctrl:1
	v_add_f32_dpp v188, v188, v188 quad_perm:[2,3,0,1] row_mask:0xf bank_mask:0xf bound_ctrl:1
	v_pk_fma_f32 v[194:195], v[32:33], v[164:165], v[158:159]
	ds_write_b32 v193, v192 offset:3072
	v_add_f32_dpp v188, v188, v188 row_half_mirror row_mask:0xf bank_mask:0xf bound_ctrl:1
	v_pk_fma_f32 v[214:215], v[34:35], v[166:167], v[182:183]
	s_nop 0
	v_add_f32_dpp v188, v188, v188 row_mirror row_mask:0xf bank_mask:0xf bound_ctrl:1
	v_pk_fma_f32 v[32:33], v[168:169], v[188:189], v[194:195] op_sel_hi:[1,0,1]
	v_pk_fma_f32 v[34:35], v[170:171], v[188:189], v[214:215] op_sel_hi:[1,0,1]
	s_waitcnt lgkmcnt(8)
; DEVI void rwkv_scan_item(int TID_, int BID_, PREF p, int g, int item, char* shm) {
;     ...
;       for (int s = 0; s < TB; ++s) {
;         OpsR c = n1;
;         n1 = n2;
;         if (s + 2 < TB) n2 = ld(ob, vb, s + 2);
;         f2v a01 = {c.a.x, c.a.y}, a23 = {c.a.z, c.a.w}, w01 = {c.w.x, c.w.y}, w23 = {c.w.z, c.w.w},
;             b01 = {c.b.x, c.b.y}, b23 = {c.b.z, c.b.w}, k01 = {c.k.x, c.k.y}, k23 = {c.k.z, c.k.w},
;             r01 = {c.r.x, c.r.y}, r23 = {c.r.z, c.r.w};
;         f2v vv = {c.v, c.v};
;         f2v vk01 = vv * k01, vk23 = vv * k23;
;         f2v t = S01 * a01;
;         t = S23 * a23 + t;
;         float sa = allreduce16(t.x + t.y);
;         f2v sv = {sa, sa};
;         S01 = S01 * w01 + (sv * b01 + vk01);
;         S23 = S23 * w23 + (sv * b23 + vk23);
;         f2v u = S01 * r01;
;         u = S23 * r23 + u;
;         float uu = u.x + u.y;
;         uu += dppmov<0xB1>(uu);
;         yb[s * 128] = uu;
;       }
	v_pk_mul_f32 v[186:187], v[32:33], v[216:217]
	v_pk_mul_f32 v[190:191], v[32:33], v[176:177]
	v_pk_fma_f32 v[186:187], v[34:35], v[218:219], v[186:187]
	v_pk_fma_f32 v[190:191], v[34:35], v[178:179], v[190:191]
	ds_read_b128 v[160:163], v237 offset:12800
	ds_read_b128 v[164:167], v237 offset:12816
	ds_read_b128 v[168:171], v237 offset:12832
	ds_read_b128 v[172:175], v237 offset:12848
	ds_read_b128 v[176:179], v237 offset:12864
	ds_read_b32 v180, v238 offset:640
	v_add_f32_e32 v188, v186, v187
	v_pk_mul_f32 v[158:159], v[228:229], v[184:185] op_sel_hi:[1,0]
	v_add_f32_e32 v192, v190, v191
	v_add_f32_dpp v188, v188, v188 quad_perm:[1,0,3,2] row_mask:0xf bank_mask:0xf bound_ctrl:1
	v_pk_mul_f32 v[182:183], v[230:231], v[184:185] op_sel_hi:[1,0]
	v_add_f32_dpp v192, v192, v192 quad_perm:[1,0,3,2] row_mask:0xf bank_mask:0xf bound_ctrl:1
	v_add_f32_dpp v188, v188, v188 quad_perm:[2,3,0,1] row_mask:0xf bank_mask:0xf bound_ctrl:1
	v_pk_fma_f32 v[194:195], v[32:33], v[220:221], v[158:159]
	ds_write_b32 v193, v192 offset:3584
	v_add_f32_dpp v188, v188, v188 row_half_mirror row_mask:0xf bank_mask:0xf bound_ctrl:1
	v_pk_fma_f32 v[214:215], v[34:35], v[222:223], v[182:183]
	s_nop 0
	v_add_f32_dpp v188, v188, v188 row_mirror row_mask:0xf bank_mask:0xf bound_ctrl:1
	v_pk_fma_f32 v[32:33], v[224:225], v[188:189], v[194:195] op_sel_hi:[1,0,1]
	v_pk_fma_f32 v[34:35], v[226:227], v[188:189], v[214:215] op_sel_hi:[1,0,1]
	s_waitcnt lgkmcnt(8)
	v_pk_mul_f32 v[186:187], v[32:33], v[136:137]
	v_pk_mul_f32 v[190:191], v[32:33], v[232:233]
	v_pk_fma_f32 v[186:187], v[34:35], v[138:139], v[186:187]
	v_pk_fma_f32 v[190:191], v[34:35], v[234:235], v[190:191]
	ds_read_b128 v[216:219], v237 offset:14080
	ds_read_b128 v[220:223], v237 offset:14096
	ds_read_b128 v[224:227], v237 offset:14112
	ds_read_b128 v[228:231], v237 offset:14128
	ds_read_b128 v[232:235], v237 offset:14144
	ds_read_b32 v184, v238 offset:704
	v_add_f32_e32 v188, v186, v187
	v_pk_mul_f32 v[158:159], v[148:149], v[156:157] op_sel_hi:[1,0]
	v_add_f32_e32 v192, v190, v191
	v_add_f32_dpp v188, v188, v188 quad_perm:[1,0,3,2] row_mask:0xf bank_mask:0xf bound_ctrl:1
	v_pk_mul_f32 v[182:183], v[150:151], v[156:157] op_sel_hi:[1,0]
	v_add_f32_dpp v192, v192, v192 quad_perm:[1,0,3,2] row_mask:0xf bank_mask:0xf bound_ctrl:1
	v_add_f32_dpp v188, v188, v188 quad_perm:[2,3,0,1] row_mask:0xf bank_mask:0xf bound_ctrl:1
	v_pk_fma_f32 v[194:195], v[32:33], v[140:141], v[158:159]
	ds_write_b32 v193, v192 offset:4096
	v_add_f32_dpp v188, v188, v188 row_half_mirror row_mask:0xf bank_mask:0xf bound_ctrl:1
	v_pk_fma_f32 v[214:215], v[34:35], v[142:143], v[182:183]
	s_nop 0
	v_add_f32_dpp v188, v188, v188 row_mirror row_mask:0xf bank_mask:0xf bound_ctrl:1
	v_pk_fma_f32 v[32:33], v[144:145], v[188:189], v[194:195] op_sel_hi:[1,0,1]
	v_pk_fma_f32 v[34:35], v[146:147], v[188:189], v[214:215] op_sel_hi:[1,0,1]
	s_waitcnt lgkmcnt(8)
	v_pk_mul_f32 v[186:187], v[32:33], v[160:161]
	v_pk_mul_f32 v[190:191], v[32:33], v[152:153]
	v_pk_fma_f32 v[186:187], v[34:35], v[162:163], v[186:187]
	v_pk_fma_f32 v[190:191], v[34:35], v[154:155], v[190:191]
	ds_read_b128 v[136:139], v237 offset:15360
	ds_read_b128 v[140:143], v237 offset:15376
	ds_read_b128 v[144:147], v237 offset:15392
	ds_read_b128 v[148:151], v237 offset:15408
	ds_read_b128 v[152:155], v237 offset:15424
	ds_read_b32 v156, v238 offset:768
	v_add_f32_e32 v188, v186, v187
	v_pk_mul_f32 v[158:159], v[172:173], v[180:181] op_sel_hi:[1,0]
	v_add_f32_e32 v192, v190, v191
	v_add_f32_dpp v188, v188, v188 quad_perm:[1,0,3,2] row_mask:0xf bank_mask:0xf bound_ctrl:1
	v_pk_mul_f32 v[182:183], v[174:175], v[180:181] op_sel_hi:[1,0]
	v_add_f32_dpp v192, v192, v192 quad_perm:[1,0,3,2] row_mask:0xf bank_mask:0xf bound_ctrl:1
	v_add_f32_dpp v188, v188, v188 quad_perm:[2,3,0,1] row_mask:0xf bank_mask:0xf bound_ctrl:1
	v_pk_fma_f32 v[194:195], v[32:33], v[164:165], v[158:159]
	ds_write_b32 v193, v192 offset:4608
	v_add_f32_dpp v188, v188, v188 row_half_mirror row_mask:0xf bank_mask:0xf bound_ctrl:1
	v_pk_fma_f32 v[214:215], v[34:35], v[166:167], v[182:183]
	s_nop 0
	v_add_f32_dpp v188, v188, v188 row_mirror row_mask:0xf bank_mask:0xf bound_ctrl:1
	v_pk_fma_f32 v[32:33], v[168:169], v[188:189], v[194:195] op_sel_hi:[1,0,1]
	v_pk_fma_f32 v[34:35], v[170:171], v[188:189], v[214:215] op_sel_hi:[1,0,1]
	s_waitcnt lgkmcnt(8)
	v_pk_mul_f32 v[186:187], v[32:33], v[216:217]
	v_pk_mul_f32 v[190:191], v[32:33], v[176:177]
	v_pk_fma_f32 v[186:187], v[34:35], v[218:219], v[186:187]
	v_pk_fma_f32 v[190:191], v[34:35], v[178:179], v[190:191]
	ds_read_b128 v[160:163], v237 offset:16640
	ds_read_b128 v[164:167], v237 offset:16656
	ds_read_b128 v[168:171], v237 offset:16672
	ds_read_b128 v[172:175], v237 offset:16688
	ds_read_b128 v[176:179], v237 offset:16704
	ds_read_b32 v180, v238 offset:832
	v_add_f32_e32 v188, v186, v187
	v_pk_mul_f32 v[158:159], v[228:229], v[184:185] op_sel_hi:[1,0]
	v_add_f32_e32 v192, v190, v191
	v_add_f32_dpp v188, v188, v188 quad_perm:[1,0,3,2] row_mask:0xf bank_mask:0xf bound_ctrl:1
	v_pk_mul_f32 v[182:183], v[230:231], v[184:185] op_sel_hi:[1,0]
	v_add_f32_dpp v192, v192, v192 quad_perm:[1,0,3,2] row_mask:0xf bank_mask:0xf bound_ctrl:1
	v_add_f32_dpp v188, v188, v188 quad_perm:[2,3,0,1] row_mask:0xf bank_mask:0xf bound_ctrl:1
	v_pk_fma_f32 v[194:195], v[32:33], v[220:221], v[158:159]
	ds_write_b32 v193, v192 offset:5120
	v_add_f32_dpp v188, v188, v188 row_half_mirror row_mask:0xf bank_mask:0xf bound_ctrl:1
	v_pk_fma_f32 v[214:215], v[34:35], v[222:223], v[182:183]
	s_nop 0
	v_add_f32_dpp v188, v188, v188 row_mirror row_mask:0xf bank_mask:0xf bound_ctrl:1
	v_pk_fma_f32 v[32:33], v[224:225], v[188:189], v[194:195] op_sel_hi:[1,0,1]
	v_pk_fma_f32 v[34:35], v[226:227], v[188:189], v[214:215] op_sel_hi:[1,0,1]
	s_waitcnt lgkmcnt(8)
; DEVI void rwkv_scan_item(int TID_, int BID_, PREF p, int g, int item, char* shm) {
;     ...
;       for (int s = 0; s < TB; ++s) {
;         OpsR c = n1;
;         n1 = n2;
;         if (s + 2 < TB) n2 = ld(ob, vb, s + 2);
;         f2v a01 = {c.a.x, c.a.y}, a23 = {c.a.z, c.a.w}, w01 = {c.w.x, c.w.y}, w23 = {c.w.z, c.w.w},
;             b01 = {c.b.x, c.b.y}, b23 = {c.b.z, c.b.w}, k01 = {c.k.x, c.k.y}, k23 = {c.k.z, c.k.w},
;             r01 = {c.r.x, c.r.y}, r23 = {c.r.z, c.r.w};
;         f2v vv = {c.v, c.v};
;         f2v vk01 = vv * k01, vk23 = vv * k23;
;         f2v t = S01 * a01;
;         t = S23 * a23 + t;
;         float sa = allreduce16(t.x + t.y);
;         f2v sv = {sa, sa};
;         S01 = S01 * w01 + (sv * b01 + vk01);
;         S23 = S23 * w23 + (sv * b23 + vk23);
;         f2v u = S01 * r01;
;         u = S23 * r23 + u;
;         float uu = u.x + u.y;
;         uu += dppmov<0xB1>(uu);
;         yb[s * 128] = uu;
;       }
	v_pk_mul_f32 v[186:187], v[32:33], v[136:137]
	v_pk_mul_f32 v[190:191], v[32:33], v[232:233]
	v_pk_fma_f32 v[186:187], v[34:35], v[138:139], v[186:187]
	v_pk_fma_f32 v[190:191], v[34:35], v[234:235], v[190:191]
	ds_read_b128 v[216:219], v237 offset:17920
	ds_read_b128 v[220:223], v237 offset:17936
	ds_read_b128 v[224:227], v237 offset:17952
	ds_read_b128 v[228:231], v237 offset:17968
	ds_read_b128 v[232:235], v237 offset:17984
	ds_read_b32 v184, v238 offset:896
	v_add_f32_e32 v188, v186, v187
	v_pk_mul_f32 v[158:159], v[148:149], v[156:157] op_sel_hi:[1,0]
	v_add_f32_e32 v192, v190, v191
	v_add_f32_dpp v188, v188, v188 quad_perm:[1,0,3,2] row_mask:0xf bank_mask:0xf bound_ctrl:1
	v_pk_mul_f32 v[182:183], v[150:151], v[156:157] op_sel_hi:[1,0]
	v_add_f32_dpp v192, v192, v192 quad_perm:[1,0,3,2] row_mask:0xf bank_mask:0xf bound_ctrl:1
	v_add_f32_dpp v188, v188, v188 quad_perm:[2,3,0,1] row_mask:0xf bank_mask:0xf bound_ctrl:1
	v_pk_fma_f32 v[194:195], v[32:33], v[140:141], v[158:159]
	ds_write_b32 v193, v192 offset:5632
	v_add_f32_dpp v188, v188, v188 row_half_mirror row_mask:0xf bank_mask:0xf bound_ctrl:1
	v_pk_fma_f32 v[214:215], v[34:35], v[142:143], v[182:183]
	s_nop 0
	v_add_f32_dpp v188, v188, v188 row_mirror row_mask:0xf bank_mask:0xf bound_ctrl:1
	v_pk_fma_f32 v[32:33], v[144:145], v[188:189], v[194:195] op_sel_hi:[1,0,1]
	v_pk_fma_f32 v[34:35], v[146:147], v[188:189], v[214:215] op_sel_hi:[1,0,1]
	s_waitcnt lgkmcnt(8)
	v_pk_mul_f32 v[186:187], v[32:33], v[160:161]
	v_pk_mul_f32 v[190:191], v[32:33], v[152:153]
	v_pk_fma_f32 v[186:187], v[34:35], v[162:163], v[186:187]
	v_pk_fma_f32 v[190:191], v[34:35], v[154:155], v[190:191]
	ds_read_b128 v[136:139], v237 offset:19200
	ds_read_b128 v[140:143], v237 offset:19216
	ds_read_b128 v[144:147], v237 offset:19232
	ds_read_b128 v[148:151], v237 offset:19248
	ds_read_b128 v[152:155], v237 offset:19264
	ds_read_b32 v156, v238 offset:960
	v_add_f32_e32 v188, v186, v187
	v_pk_mul_f32 v[158:159], v[172:173], v[180:181] op_sel_hi:[1,0]
	v_add_f32_e32 v192, v190, v191
	v_add_f32_dpp v188, v188, v188 quad_perm:[1,0,3,2] row_mask:0xf bank_mask:0xf bound_ctrl:1
	v_pk_mul_f32 v[182:183], v[174:175], v[180:181] op_sel_hi:[1,0]
	v_add_f32_dpp v192, v192, v192 quad_perm:[1,0,3,2] row_mask:0xf bank_mask:0xf bound_ctrl:1
	v_add_f32_dpp v188, v188, v188 quad_perm:[2,3,0,1] row_mask:0xf bank_mask:0xf bound_ctrl:1
	v_pk_fma_f32 v[194:195], v[32:33], v[164:165], v[158:159]
	ds_write_b32 v193, v192 offset:6144
	v_add_f32_dpp v188, v188, v188 row_half_mirror row_mask:0xf bank_mask:0xf bound_ctrl:1
	v_pk_fma_f32 v[214:215], v[34:35], v[166:167], v[182:183]
	s_nop 0
	v_add_f32_dpp v188, v188, v188 row_mirror row_mask:0xf bank_mask:0xf bound_ctrl:1
	v_pk_fma_f32 v[32:33], v[168:169], v[188:189], v[194:195] op_sel_hi:[1,0,1]
	v_pk_fma_f32 v[34:35], v[170:171], v[188:189], v[214:215] op_sel_hi:[1,0,1]
	s_waitcnt lgkmcnt(8)
	v_pk_mul_f32 v[186:187], v[32:33], v[216:217]
	v_pk_mul_f32 v[190:191], v[32:33], v[176:177]
	v_pk_fma_f32 v[186:187], v[34:35], v[218:219], v[186:187]
	v_pk_fma_f32 v[190:191], v[34:35], v[178:179], v[190:191]
	ds_read_b128 v[160:163], v237 offset:20480
	ds_read_b128 v[164:167], v237 offset:20496
	ds_read_b128 v[168:171], v237 offset:20512
	ds_read_b128 v[172:175], v237 offset:20528
	ds_read_b128 v[176:179], v237 offset:20544
	ds_read_b32 v180, v238 offset:1024
	v_add_f32_e32 v188, v186, v187
	v_pk_mul_f32 v[158:159], v[228:229], v[184:185] op_sel_hi:[1,0]
	v_add_f32_e32 v192, v190, v191
	v_add_f32_dpp v188, v188, v188 quad_perm:[1,0,3,2] row_mask:0xf bank_mask:0xf bound_ctrl:1
	v_pk_mul_f32 v[182:183], v[230:231], v[184:185] op_sel_hi:[1,0]
	v_add_f32_dpp v192, v192, v192 quad_perm:[1,0,3,2] row_mask:0xf bank_mask:0xf bound_ctrl:1
	v_add_f32_dpp v188, v188, v188 quad_perm:[2,3,0,1] row_mask:0xf bank_mask:0xf bound_ctrl:1
	v_pk_fma_f32 v[194:195], v[32:33], v[220:221], v[158:159]
	ds_write_b32 v193, v192 offset:6656
	v_add_f32_dpp v188, v188, v188 row_half_mirror row_mask:0xf bank_mask:0xf bound_ctrl:1
	v_pk_fma_f32 v[214:215], v[34:35], v[222:223], v[182:183]
	s_nop 0
	v_add_f32_dpp v188, v188, v188 row_mirror row_mask:0xf bank_mask:0xf bound_ctrl:1
	v_pk_fma_f32 v[32:33], v[224:225], v[188:189], v[194:195] op_sel_hi:[1,0,1]
	v_pk_fma_f32 v[34:35], v[226:227], v[188:189], v[214:215] op_sel_hi:[1,0,1]
	s_waitcnt lgkmcnt(8)
	v_pk_mul_f32 v[186:187], v[32:33], v[136:137]
	v_pk_mul_f32 v[190:191], v[32:33], v[232:233]
	v_pk_fma_f32 v[186:187], v[34:35], v[138:139], v[186:187]
	v_pk_fma_f32 v[190:191], v[34:35], v[234:235], v[190:191]
	ds_read_b128 v[216:219], v237 offset:21760
	ds_read_b128 v[220:223], v237 offset:21776
	ds_read_b128 v[224:227], v237 offset:21792
	ds_read_b128 v[228:231], v237 offset:21808
	ds_read_b128 v[232:235], v237 offset:21824
	ds_read_b32 v184, v238 offset:1088
	v_add_f32_e32 v188, v186, v187
	v_pk_mul_f32 v[158:159], v[148:149], v[156:157] op_sel_hi:[1,0]
	v_add_f32_e32 v192, v190, v191
	v_add_f32_dpp v188, v188, v188 quad_perm:[1,0,3,2] row_mask:0xf bank_mask:0xf bound_ctrl:1
	v_pk_mul_f32 v[182:183], v[150:151], v[156:157] op_sel_hi:[1,0]
	v_add_f32_dpp v192, v192, v192 quad_perm:[1,0,3,2] row_mask:0xf bank_mask:0xf bound_ctrl:1
	v_add_f32_dpp v188, v188, v188 quad_perm:[2,3,0,1] row_mask:0xf bank_mask:0xf bound_ctrl:1
	v_pk_fma_f32 v[194:195], v[32:33], v[140:141], v[158:159]
	ds_write_b32 v193, v192 offset:7168
	v_add_f32_dpp v188, v188, v188 row_half_mirror row_mask:0xf bank_mask:0xf bound_ctrl:1
	v_pk_fma_f32 v[214:215], v[34:35], v[142:143], v[182:183]
	s_nop 0
	v_add_f32_dpp v188, v188, v188 row_mirror row_mask:0xf bank_mask:0xf bound_ctrl:1
	v_pk_fma_f32 v[32:33], v[144:145], v[188:189], v[194:195] op_sel_hi:[1,0,1]
	v_pk_fma_f32 v[34:35], v[146:147], v[188:189], v[214:215] op_sel_hi:[1,0,1]
	s_waitcnt lgkmcnt(8)
; DEVI void rwkv_scan_item(int TID_, int BID_, PREF p, int g, int item, char* shm) {
;     ...
;       for (int s = 0; s < TB; ++s) {
;         OpsR c = n1;
;         n1 = n2;
;         if (s + 2 < TB) n2 = ld(ob, vb, s + 2);
;         f2v a01 = {c.a.x, c.a.y}, a23 = {c.a.z, c.a.w}, w01 = {c.w.x, c.w.y}, w23 = {c.w.z, c.w.w},
;             b01 = {c.b.x, c.b.y}, b23 = {c.b.z, c.b.w}, k01 = {c.k.x, c.k.y}, k23 = {c.k.z, c.k.w},
;             r01 = {c.r.x, c.r.y}, r23 = {c.r.z, c.r.w};
;         f2v vv = {c.v, c.v};
;         f2v vk01 = vv * k01, vk23 = vv * k23;
;         f2v t = S01 * a01;
;         t = S23 * a23 + t;
;         float sa = allreduce16(t.x + t.y);
;         f2v sv = {sa, sa};
;         S01 = S01 * w01 + (sv * b01 + vk01);
;         S23 = S23 * w23 + (sv * b23 + vk23);
;         f2v u = S01 * r01;
;         u = S23 * r23 + u;
;         float uu = u.x + u.y;
;         uu += dppmov<0xB1>(uu);
;         yb[s * 128] = uu;
;       }
	v_pk_mul_f32 v[186:187], v[32:33], v[160:161]
	v_pk_mul_f32 v[190:191], v[32:33], v[152:153]
	v_pk_fma_f32 v[186:187], v[34:35], v[162:163], v[186:187]
	v_pk_fma_f32 v[190:191], v[34:35], v[154:155], v[190:191]
	ds_read_b128 v[136:139], v237 offset:23040
	ds_read_b128 v[140:143], v237 offset:23056
	ds_read_b128 v[144:147], v237 offset:23072
	ds_read_b128 v[148:151], v237 offset:23088
	ds_read_b128 v[152:155], v237 offset:23104
	ds_read_b32 v156, v238 offset:1152
	v_add_f32_e32 v188, v186, v187
	v_pk_mul_f32 v[158:159], v[172:173], v[180:181] op_sel_hi:[1,0]
	v_add_f32_e32 v192, v190, v191
	v_add_f32_dpp v188, v188, v188 quad_perm:[1,0,3,2] row_mask:0xf bank_mask:0xf bound_ctrl:1
	v_pk_mul_f32 v[182:183], v[174:175], v[180:181] op_sel_hi:[1,0]
	v_add_f32_dpp v192, v192, v192 quad_perm:[1,0,3,2] row_mask:0xf bank_mask:0xf bound_ctrl:1
	v_add_f32_dpp v188, v188, v188 quad_perm:[2,3,0,1] row_mask:0xf bank_mask:0xf bound_ctrl:1
	v_pk_fma_f32 v[194:195], v[32:33], v[164:165], v[158:159]
	ds_write_b32 v193, v192 offset:7680
	v_add_f32_dpp v188, v188, v188 row_half_mirror row_mask:0xf bank_mask:0xf bound_ctrl:1
	v_pk_fma_f32 v[214:215], v[34:35], v[166:167], v[182:183]
	s_nop 0
	v_add_f32_dpp v188, v188, v188 row_mirror row_mask:0xf bank_mask:0xf bound_ctrl:1
	v_pk_fma_f32 v[32:33], v[168:169], v[188:189], v[194:195] op_sel_hi:[1,0,1]
	v_pk_fma_f32 v[34:35], v[170:171], v[188:189], v[214:215] op_sel_hi:[1,0,1]
	s_waitcnt lgkmcnt(8)
	v_pk_mul_f32 v[186:187], v[32:33], v[216:217]
	v_pk_mul_f32 v[190:191], v[32:33], v[176:177]
	v_pk_fma_f32 v[186:187], v[34:35], v[218:219], v[186:187]
	v_pk_fma_f32 v[190:191], v[34:35], v[178:179], v[190:191]
	ds_read_b128 v[160:163], v237 offset:24320
	ds_read_b128 v[164:167], v237 offset:24336
	ds_read_b128 v[168:171], v237 offset:24352
	ds_read_b128 v[172:175], v237 offset:24368
	ds_read_b128 v[176:179], v237 offset:24384
	ds_read_b32 v180, v238 offset:1216
	v_add_f32_e32 v188, v186, v187
	v_pk_mul_f32 v[158:159], v[228:229], v[184:185] op_sel_hi:[1,0]
	v_add_f32_e32 v192, v190, v191
	v_add_f32_dpp v188, v188, v188 quad_perm:[1,0,3,2] row_mask:0xf bank_mask:0xf bound_ctrl:1
	v_pk_mul_f32 v[182:183], v[230:231], v[184:185] op_sel_hi:[1,0]
	v_add_f32_dpp v192, v192, v192 quad_perm:[1,0,3,2] row_mask:0xf bank_mask:0xf bound_ctrl:1
	v_add_f32_dpp v188, v188, v188 quad_perm:[2,3,0,1] row_mask:0xf bank_mask:0xf bound_ctrl:1
	v_pk_fma_f32 v[194:195], v[32:33], v[220:221], v[158:159]
	ds_write_b32 v193, v192 offset:8192
	v_add_f32_dpp v188, v188, v188 row_half_mirror row_mask:0xf bank_mask:0xf bound_ctrl:1
	v_pk_fma_f32 v[214:215], v[34:35], v[222:223], v[182:183]
	s_nop 0
	v_add_f32_dpp v188, v188, v188 row_mirror row_mask:0xf bank_mask:0xf bound_ctrl:1
	v_pk_fma_f32 v[32:33], v[224:225], v[188:189], v[194:195] op_sel_hi:[1,0,1]
	v_pk_fma_f32 v[34:35], v[226:227], v[188:189], v[214:215] op_sel_hi:[1,0,1]
	s_waitcnt lgkmcnt(8)
	v_pk_mul_f32 v[186:187], v[32:33], v[136:137]
	v_pk_mul_f32 v[190:191], v[32:33], v[232:233]
	v_pk_fma_f32 v[186:187], v[34:35], v[138:139], v[186:187]
	v_pk_fma_f32 v[190:191], v[34:35], v[234:235], v[190:191]
	ds_read_b128 v[216:219], v237 offset:25600
	ds_read_b128 v[220:223], v237 offset:25616
	ds_read_b128 v[224:227], v237 offset:25632
	ds_read_b128 v[228:231], v237 offset:25648
	ds_read_b128 v[232:235], v237 offset:25664
	ds_read_b32 v184, v238 offset:1280
	v_add_f32_e32 v188, v186, v187
	v_pk_mul_f32 v[158:159], v[148:149], v[156:157] op_sel_hi:[1,0]
	v_add_f32_e32 v192, v190, v191
	v_add_f32_dpp v188, v188, v188 quad_perm:[1,0,3,2] row_mask:0xf bank_mask:0xf bound_ctrl:1
	v_pk_mul_f32 v[182:183], v[150:151], v[156:157] op_sel_hi:[1,0]
	v_add_f32_dpp v192, v192, v192 quad_perm:[1,0,3,2] row_mask:0xf bank_mask:0xf bound_ctrl:1
	v_add_f32_dpp v188, v188, v188 quad_perm:[2,3,0,1] row_mask:0xf bank_mask:0xf bound_ctrl:1
	v_pk_fma_f32 v[194:195], v[32:33], v[140:141], v[158:159]
	ds_write_b32 v193, v192 offset:8704
	v_add_f32_dpp v188, v188, v188 row_half_mirror row_mask:0xf bank_mask:0xf bound_ctrl:1
	v_pk_fma_f32 v[214:215], v[34:35], v[142:143], v[182:183]
	s_nop 0
	v_add_f32_dpp v188, v188, v188 row_mirror row_mask:0xf bank_mask:0xf bound_ctrl:1
	v_pk_fma_f32 v[32:33], v[144:145], v[188:189], v[194:195] op_sel_hi:[1,0,1]
	v_pk_fma_f32 v[34:35], v[146:147], v[188:189], v[214:215] op_sel_hi:[1,0,1]
	s_waitcnt lgkmcnt(8)
	v_pk_mul_f32 v[186:187], v[32:33], v[160:161]
	v_pk_mul_f32 v[190:191], v[32:33], v[152:153]
	v_pk_fma_f32 v[186:187], v[34:35], v[162:163], v[186:187]
	v_pk_fma_f32 v[190:191], v[34:35], v[154:155], v[190:191]
	ds_read_b128 v[136:139], v237 offset:26880
	ds_read_b128 v[140:143], v237 offset:26896
	ds_read_b128 v[144:147], v237 offset:26912
	ds_read_b128 v[148:151], v237 offset:26928
	ds_read_b128 v[152:155], v237 offset:26944
	ds_read_b32 v156, v238 offset:1344
	v_add_f32_e32 v188, v186, v187
	v_pk_mul_f32 v[158:159], v[172:173], v[180:181] op_sel_hi:[1,0]
	v_add_f32_e32 v192, v190, v191
	v_add_f32_dpp v188, v188, v188 quad_perm:[1,0,3,2] row_mask:0xf bank_mask:0xf bound_ctrl:1
	v_pk_mul_f32 v[182:183], v[174:175], v[180:181] op_sel_hi:[1,0]
	v_add_f32_dpp v192, v192, v192 quad_perm:[1,0,3,2] row_mask:0xf bank_mask:0xf bound_ctrl:1
	v_add_f32_dpp v188, v188, v188 quad_perm:[2,3,0,1] row_mask:0xf bank_mask:0xf bound_ctrl:1
	v_pk_fma_f32 v[194:195], v[32:33], v[164:165], v[158:159]
	ds_write_b32 v193, v192 offset:9216
	v_add_f32_dpp v188, v188, v188 row_half_mirror row_mask:0xf bank_mask:0xf bound_ctrl:1
	v_pk_fma_f32 v[214:215], v[34:35], v[166:167], v[182:183]
	s_nop 0
	v_add_f32_dpp v188, v188, v188 row_mirror row_mask:0xf bank_mask:0xf bound_ctrl:1
	v_pk_fma_f32 v[32:33], v[168:169], v[188:189], v[194:195] op_sel_hi:[1,0,1]
	v_pk_fma_f32 v[34:35], v[170:171], v[188:189], v[214:215] op_sel_hi:[1,0,1]
	s_waitcnt lgkmcnt(8)
; DEVI void rwkv_scan_item(int TID_, int BID_, PREF p, int g, int item, char* shm) {
;     ...
;     const float* q = ob + s * 16 * 20;
;     o.a = *(const float4*)(q + 0); o.w = *(const float4*)(q + 4); o.b = *(const float4*)(q + 8);
;     o.k = *(const float4*)(q + 12); o.r = *(const float4*)(q + 16);
;     o.v = vb[s * 16];
;     return o;
;     ...
;       for (int s = 0; s < TB; ++s) {
;         OpsR c = n1;
;         n1 = n2;
;         if (s + 2 < TB) n2 = ld(ob, vb, s + 2);
;         f2v a01 = {c.a.x, c.a.y}, a23 = {c.a.z, c.a.w}, w01 = {c.w.x, c.w.y}, w23 = {c.w.z, c.w.w},
;             b01 = {c.b.x, c.b.y}, b23 = {c.b.z, c.b.w}, k01 = {c.k.x, c.k.y}, k23 = {c.k.z, c.k.w},
;             r01 = {c.r.x, c.r.y}, r23 = {c.r.z, c.r.w};
;         f2v vv = {c.v, c.v};
;         f2v vk01 = vv * k01, vk23 = vv * k23;
;         f2v t = S01 * a01;
;         t = S23 * a23 + t;
;         float sa = allreduce16(t.x + t.y);
;         f2v sv = {sa, sa};
;         S01 = S01 * w01 + (sv * b01 + vk01);
;         S23 = S23 * w23 + (sv * b23 + vk23);
;         f2v u = S01 * r01;
;         u = S23 * r23 + u;
;         float uu = u.x + u.y;
;         uu += dppmov<0xB1>(uu);
;         yb[s * 128] = uu;
;       }
	v_pk_mul_f32 v[186:187], v[32:33], v[216:217]
	v_pk_mul_f32 v[190:191], v[32:33], v[176:177]
	v_pk_fma_f32 v[186:187], v[34:35], v[218:219], v[186:187]
	v_pk_fma_f32 v[190:191], v[34:35], v[178:179], v[190:191]
	ds_read_b128 v[160:163], v237 offset:28160
	ds_read_b128 v[164:167], v237 offset:28176
	ds_read_b128 v[168:171], v237 offset:28192
	ds_read_b128 v[172:175], v237 offset:28208
	ds_read_b128 v[176:179], v237 offset:28224
	ds_read_b32 v180, v238 offset:1408
	v_add_f32_e32 v188, v186, v187
	v_pk_mul_f32 v[158:159], v[228:229], v[184:185] op_sel_hi:[1,0]
	v_add_f32_e32 v192, v190, v191
	v_add_f32_dpp v188, v188, v188 quad_perm:[1,0,3,2] row_mask:0xf bank_mask:0xf bound_ctrl:1
	v_pk_mul_f32 v[182:183], v[230:231], v[184:185] op_sel_hi:[1,0]
	v_add_f32_dpp v192, v192, v192 quad_perm:[1,0,3,2] row_mask:0xf bank_mask:0xf bound_ctrl:1
	v_add_f32_dpp v188, v188, v188 quad_perm:[2,3,0,1] row_mask:0xf bank_mask:0xf bound_ctrl:1
	v_pk_fma_f32 v[194:195], v[32:33], v[220:221], v[158:159]
	ds_write_b32 v193, v192 offset:9728
	v_add_f32_dpp v188, v188, v188 row_half_mirror row_mask:0xf bank_mask:0xf bound_ctrl:1
	v_pk_fma_f32 v[214:215], v[34:35], v[222:223], v[182:183]
	s_nop 0
	v_add_f32_dpp v188, v188, v188 row_mirror row_mask:0xf bank_mask:0xf bound_ctrl:1
	v_pk_fma_f32 v[32:33], v[224:225], v[188:189], v[194:195] op_sel_hi:[1,0,1]
	v_pk_fma_f32 v[34:35], v[226:227], v[188:189], v[214:215] op_sel_hi:[1,0,1]
	s_waitcnt lgkmcnt(8)
	v_pk_mul_f32 v[186:187], v[32:33], v[136:137]
	v_pk_mul_f32 v[190:191], v[32:33], v[232:233]
	v_pk_fma_f32 v[186:187], v[34:35], v[138:139], v[186:187]
	v_pk_fma_f32 v[190:191], v[34:35], v[234:235], v[190:191]
	ds_read_b128 v[216:219], v237 offset:29440
	ds_read_b128 v[220:223], v237 offset:29456
	ds_read_b128 v[224:227], v237 offset:29472
	ds_read_b128 v[228:231], v237 offset:29488
	ds_read_b128 v[232:235], v237 offset:29504
	ds_read_b32 v184, v238 offset:1472
	v_add_f32_e32 v188, v186, v187
	v_pk_mul_f32 v[158:159], v[148:149], v[156:157] op_sel_hi:[1,0]
	v_add_f32_e32 v192, v190, v191
	v_add_f32_dpp v188, v188, v188 quad_perm:[1,0,3,2] row_mask:0xf bank_mask:0xf bound_ctrl:1
	v_pk_mul_f32 v[182:183], v[150:151], v[156:157] op_sel_hi:[1,0]
	v_add_f32_dpp v192, v192, v192 quad_perm:[1,0,3,2] row_mask:0xf bank_mask:0xf bound_ctrl:1
	v_add_f32_dpp v188, v188, v188 quad_perm:[2,3,0,1] row_mask:0xf bank_mask:0xf bound_ctrl:1
	v_pk_fma_f32 v[194:195], v[32:33], v[140:141], v[158:159]
	ds_write_b32 v193, v192 offset:10240
	v_add_f32_dpp v188, v188, v188 row_half_mirror row_mask:0xf bank_mask:0xf bound_ctrl:1
	v_pk_fma_f32 v[214:215], v[34:35], v[142:143], v[182:183]
	s_nop 0
	v_add_f32_dpp v188, v188, v188 row_mirror row_mask:0xf bank_mask:0xf bound_ctrl:1
	v_pk_fma_f32 v[32:33], v[144:145], v[188:189], v[194:195] op_sel_hi:[1,0,1]
	v_pk_fma_f32 v[34:35], v[146:147], v[188:189], v[214:215] op_sel_hi:[1,0,1]
	s_waitcnt lgkmcnt(8)
	v_pk_mul_f32 v[186:187], v[32:33], v[160:161]
	v_pk_mul_f32 v[190:191], v[32:33], v[152:153]
	v_pk_fma_f32 v[186:187], v[34:35], v[162:163], v[186:187]
	v_pk_fma_f32 v[190:191], v[34:35], v[154:155], v[190:191]
	ds_read_b128 v[136:139], v237 offset:30720
	ds_read_b128 v[140:143], v237 offset:30736
	ds_read_b128 v[144:147], v237 offset:30752
	ds_read_b128 v[148:151], v237 offset:30768
	ds_read_b128 v[152:155], v237 offset:30784
	ds_read_b32 v156, v238 offset:1536
	v_add_f32_e32 v188, v186, v187
	v_pk_mul_f32 v[158:159], v[172:173], v[180:181] op_sel_hi:[1,0]
	v_add_f32_e32 v192, v190, v191
	v_add_f32_dpp v188, v188, v188 quad_perm:[1,0,3,2] row_mask:0xf bank_mask:0xf bound_ctrl:1
	v_pk_mul_f32 v[182:183], v[174:175], v[180:181] op_sel_hi:[1,0]
	v_add_f32_dpp v192, v192, v192 quad_perm:[1,0,3,2] row_mask:0xf bank_mask:0xf bound_ctrl:1
	v_add_f32_dpp v188, v188, v188 quad_perm:[2,3,0,1] row_mask:0xf bank_mask:0xf bound_ctrl:1
	v_pk_fma_f32 v[194:195], v[32:33], v[164:165], v[158:159]
	ds_write_b32 v193, v192 offset:10752
	v_add_f32_dpp v188, v188, v188 row_half_mirror row_mask:0xf bank_mask:0xf bound_ctrl:1
	v_pk_fma_f32 v[214:215], v[34:35], v[166:167], v[182:183]
	s_nop 0
	v_add_f32_dpp v188, v188, v188 row_mirror row_mask:0xf bank_mask:0xf bound_ctrl:1
	v_pk_fma_f32 v[32:33], v[168:169], v[188:189], v[194:195] op_sel_hi:[1,0,1]
	v_pk_fma_f32 v[34:35], v[170:171], v[188:189], v[214:215] op_sel_hi:[1,0,1]
	s_waitcnt lgkmcnt(8)
	v_pk_mul_f32 v[186:187], v[32:33], v[216:217]
	v_pk_mul_f32 v[190:191], v[32:33], v[176:177]
	v_pk_fma_f32 v[186:187], v[34:35], v[218:219], v[186:187]
	v_pk_fma_f32 v[190:191], v[34:35], v[178:179], v[190:191]
	ds_read_b128 v[160:163], v237 offset:32000
	ds_read_b128 v[164:167], v237 offset:32016
	ds_read_b128 v[168:171], v237 offset:32032
	ds_read_b128 v[172:175], v237 offset:32048
	ds_read_b128 v[176:179], v237 offset:32064
	ds_read_b32 v180, v238 offset:1600
	v_add_f32_e32 v188, v186, v187
	v_pk_mul_f32 v[158:159], v[228:229], v[184:185] op_sel_hi:[1,0]
	v_add_f32_e32 v192, v190, v191
	v_add_f32_dpp v188, v188, v188 quad_perm:[1,0,3,2] row_mask:0xf bank_mask:0xf bound_ctrl:1
	v_pk_mul_f32 v[182:183], v[230:231], v[184:185] op_sel_hi:[1,0]
	v_add_f32_dpp v192, v192, v192 quad_perm:[1,0,3,2] row_mask:0xf bank_mask:0xf bound_ctrl:1
	v_add_f32_dpp v188, v188, v188 quad_perm:[2,3,0,1] row_mask:0xf bank_mask:0xf bound_ctrl:1
	v_pk_fma_f32 v[194:195], v[32:33], v[220:221], v[158:159]
	ds_write_b32 v193, v192 offset:11264
	v_add_f32_dpp v188, v188, v188 row_half_mirror row_mask:0xf bank_mask:0xf bound_ctrl:1
	v_pk_fma_f32 v[214:215], v[34:35], v[222:223], v[182:183]
	s_nop 0
	v_add_f32_dpp v188, v188, v188 row_mirror row_mask:0xf bank_mask:0xf bound_ctrl:1
	v_pk_fma_f32 v[32:33], v[224:225], v[188:189], v[194:195] op_sel_hi:[1,0,1]
	v_pk_fma_f32 v[34:35], v[226:227], v[188:189], v[214:215] op_sel_hi:[1,0,1]
	s_waitcnt lgkmcnt(8)
; DEVI void rwkv_scan_item(int TID_, int BID_, PREF p, int g, int item, char* shm) {
;     ...
;     const float* q = ob + s * 16 * 20;
;     o.a = *(const float4*)(q + 0); o.w = *(const float4*)(q + 4); o.b = *(const float4*)(q + 8);
;     o.k = *(const float4*)(q + 12); o.r = *(const float4*)(q + 16);
;     o.v = vb[s * 16];
;     return o;
;     ...
;       for (int s = 0; s < TB; ++s) {
;         OpsR c = n1;
;         n1 = n2;
;         if (s + 2 < TB) n2 = ld(ob, vb, s + 2);
;         f2v a01 = {c.a.x, c.a.y}, a23 = {c.a.z, c.a.w}, w01 = {c.w.x, c.w.y}, w23 = {c.w.z, c.w.w},
;             b01 = {c.b.x, c.b.y}, b23 = {c.b.z, c.b.w}, k01 = {c.k.x, c.k.y}, k23 = {c.k.z, c.k.w},
;             r01 = {c.r.x, c.r.y}, r23 = {c.r.z, c.r.w};
;         f2v vv = {c.v, c.v};
;         f2v vk01 = vv * k01, vk23 = vv * k23;
;         f2v t = S01 * a01;
;         t = S23 * a23 + t;
;         float sa = allreduce16(t.x + t.y);
;         f2v sv = {sa, sa};
;         S01 = S01 * w01 + (sv * b01 + vk01);
;         S23 = S23 * w23 + (sv * b23 + vk23);
;         f2v u = S01 * r01;
;         u = S23 * r23 + u;
;         float uu = u.x + u.y;
;         uu += dppmov<0xB1>(uu);
;         yb[s * 128] = uu;
;       }
	v_pk_mul_f32 v[186:187], v[32:33], v[136:137]
	v_pk_mul_f32 v[190:191], v[32:33], v[232:233]
	v_pk_fma_f32 v[186:187], v[34:35], v[138:139], v[186:187]
	v_pk_fma_f32 v[190:191], v[34:35], v[234:235], v[190:191]
	ds_read_b128 v[216:219], v237 offset:33280
	ds_read_b128 v[220:223], v237 offset:33296
	ds_read_b128 v[224:227], v237 offset:33312
	ds_read_b128 v[228:231], v237 offset:33328
	ds_read_b128 v[232:235], v237 offset:33344
	ds_read_b32 v184, v238 offset:1664
	v_add_f32_e32 v188, v186, v187
	v_pk_mul_f32 v[158:159], v[148:149], v[156:157] op_sel_hi:[1,0]
	v_add_f32_e32 v192, v190, v191
	v_add_f32_dpp v188, v188, v188 quad_perm:[1,0,3,2] row_mask:0xf bank_mask:0xf bound_ctrl:1
	v_pk_mul_f32 v[182:183], v[150:151], v[156:157] op_sel_hi:[1,0]
	v_add_f32_dpp v192, v192, v192 quad_perm:[1,0,3,2] row_mask:0xf bank_mask:0xf bound_ctrl:1
	v_add_f32_dpp v188, v188, v188 quad_perm:[2,3,0,1] row_mask:0xf bank_mask:0xf bound_ctrl:1
	v_pk_fma_f32 v[194:195], v[32:33], v[140:141], v[158:159]
	ds_write_b32 v193, v192 offset:11776
	v_add_f32_dpp v188, v188, v188 row_half_mirror row_mask:0xf bank_mask:0xf bound_ctrl:1
	v_pk_fma_f32 v[214:215], v[34:35], v[142:143], v[182:183]
	s_nop 0
	v_add_f32_dpp v188, v188, v188 row_mirror row_mask:0xf bank_mask:0xf bound_ctrl:1
	v_pk_fma_f32 v[32:33], v[144:145], v[188:189], v[194:195] op_sel_hi:[1,0,1]
	v_pk_fma_f32 v[34:35], v[146:147], v[188:189], v[214:215] op_sel_hi:[1,0,1]
	s_waitcnt lgkmcnt(8)
	v_pk_mul_f32 v[186:187], v[32:33], v[160:161]
	v_pk_mul_f32 v[190:191], v[32:33], v[152:153]
	v_pk_fma_f32 v[186:187], v[34:35], v[162:163], v[186:187]
	v_pk_fma_f32 v[190:191], v[34:35], v[154:155], v[190:191]
	ds_read_b128 v[136:139], v237 offset:34560
	ds_read_b128 v[140:143], v237 offset:34576
	ds_read_b128 v[144:147], v237 offset:34592
	ds_read_b128 v[148:151], v237 offset:34608
	ds_read_b128 v[152:155], v237 offset:34624
	ds_read_b32 v156, v238 offset:1728
	v_add_f32_e32 v188, v186, v187
	v_pk_mul_f32 v[158:159], v[172:173], v[180:181] op_sel_hi:[1,0]
	v_add_f32_e32 v192, v190, v191
	v_add_f32_dpp v188, v188, v188 quad_perm:[1,0,3,2] row_mask:0xf bank_mask:0xf bound_ctrl:1
	v_pk_mul_f32 v[182:183], v[174:175], v[180:181] op_sel_hi:[1,0]
	v_add_f32_dpp v192, v192, v192 quad_perm:[1,0,3,2] row_mask:0xf bank_mask:0xf bound_ctrl:1
	v_add_f32_dpp v188, v188, v188 quad_perm:[2,3,0,1] row_mask:0xf bank_mask:0xf bound_ctrl:1
	v_pk_fma_f32 v[194:195], v[32:33], v[164:165], v[158:159]
	ds_write_b32 v193, v192 offset:12288
	v_add_f32_dpp v188, v188, v188 row_half_mirror row_mask:0xf bank_mask:0xf bound_ctrl:1
	v_pk_fma_f32 v[214:215], v[34:35], v[166:167], v[182:183]
	s_nop 0
	v_add_f32_dpp v188, v188, v188 row_mirror row_mask:0xf bank_mask:0xf bound_ctrl:1
	v_pk_fma_f32 v[32:33], v[168:169], v[188:189], v[194:195] op_sel_hi:[1,0,1]
	v_pk_fma_f32 v[34:35], v[170:171], v[188:189], v[214:215] op_sel_hi:[1,0,1]
	s_waitcnt lgkmcnt(8)
	v_pk_mul_f32 v[186:187], v[32:33], v[216:217]
	v_pk_mul_f32 v[190:191], v[32:33], v[176:177]
	v_pk_fma_f32 v[186:187], v[34:35], v[218:219], v[186:187]
	v_pk_fma_f32 v[190:191], v[34:35], v[178:179], v[190:191]
	ds_read_b128 v[160:163], v237 offset:35840
	ds_read_b128 v[164:167], v237 offset:35856
	ds_read_b128 v[168:171], v237 offset:35872
	ds_read_b128 v[172:175], v237 offset:35888
	ds_read_b128 v[176:179], v237 offset:35904
	ds_read_b32 v180, v238 offset:1792
	v_add_f32_e32 v188, v186, v187
	v_pk_mul_f32 v[158:159], v[228:229], v[184:185] op_sel_hi:[1,0]
	v_add_f32_e32 v192, v190, v191
	v_add_f32_dpp v188, v188, v188 quad_perm:[1,0,3,2] row_mask:0xf bank_mask:0xf bound_ctrl:1
	v_pk_mul_f32 v[182:183], v[230:231], v[184:185] op_sel_hi:[1,0]
	v_add_f32_dpp v192, v192, v192 quad_perm:[1,0,3,2] row_mask:0xf bank_mask:0xf bound_ctrl:1
	v_add_f32_dpp v188, v188, v188 quad_perm:[2,3,0,1] row_mask:0xf bank_mask:0xf bound_ctrl:1
	v_pk_fma_f32 v[194:195], v[32:33], v[220:221], v[158:159]
	ds_write_b32 v193, v192 offset:12800
	v_add_f32_dpp v188, v188, v188 row_half_mirror row_mask:0xf bank_mask:0xf bound_ctrl:1
	v_pk_fma_f32 v[214:215], v[34:35], v[222:223], v[182:183]
	s_nop 0
	v_add_f32_dpp v188, v188, v188 row_mirror row_mask:0xf bank_mask:0xf bound_ctrl:1
	v_pk_fma_f32 v[32:33], v[224:225], v[188:189], v[194:195] op_sel_hi:[1,0,1]
	v_pk_fma_f32 v[34:35], v[226:227], v[188:189], v[214:215] op_sel_hi:[1,0,1]
	s_waitcnt lgkmcnt(8)
	v_pk_mul_f32 v[186:187], v[32:33], v[136:137]
	v_pk_mul_f32 v[190:191], v[32:33], v[232:233]
	v_pk_fma_f32 v[186:187], v[34:35], v[138:139], v[186:187]
	v_pk_fma_f32 v[190:191], v[34:35], v[234:235], v[190:191]
	ds_read_b128 v[216:219], v237 offset:37120
	ds_read_b128 v[220:223], v237 offset:37136
	ds_read_b128 v[224:227], v237 offset:37152
	ds_read_b128 v[228:231], v237 offset:37168
	ds_read_b128 v[232:235], v237 offset:37184
	ds_read_b32 v184, v238 offset:1856
	v_add_f32_e32 v188, v186, v187
	v_pk_mul_f32 v[158:159], v[148:149], v[156:157] op_sel_hi:[1,0]
	v_add_f32_e32 v192, v190, v191
	v_add_f32_dpp v188, v188, v188 quad_perm:[1,0,3,2] row_mask:0xf bank_mask:0xf bound_ctrl:1
	v_pk_mul_f32 v[182:183], v[150:151], v[156:157] op_sel_hi:[1,0]
	v_add_f32_dpp v192, v192, v192 quad_perm:[1,0,3,2] row_mask:0xf bank_mask:0xf bound_ctrl:1
	v_add_f32_dpp v188, v188, v188 quad_perm:[2,3,0,1] row_mask:0xf bank_mask:0xf bound_ctrl:1
	v_pk_fma_f32 v[194:195], v[32:33], v[140:141], v[158:159]
	ds_write_b32 v193, v192 offset:13312
	v_add_f32_dpp v188, v188, v188 row_half_mirror row_mask:0xf bank_mask:0xf bound_ctrl:1
	v_pk_fma_f32 v[214:215], v[34:35], v[142:143], v[182:183]
	s_nop 0
	v_add_f32_dpp v188, v188, v188 row_mirror row_mask:0xf bank_mask:0xf bound_ctrl:1
	v_pk_fma_f32 v[32:33], v[144:145], v[188:189], v[194:195] op_sel_hi:[1,0,1]
	v_pk_fma_f32 v[34:35], v[146:147], v[188:189], v[214:215] op_sel_hi:[1,0,1]
	s_waitcnt lgkmcnt(8)
; DEVI void rwkv_scan_item(int TID_, int BID_, PREF p, int g, int item, char* shm) {
;     ...
;     const float* q = ob + s * 16 * 20;
;     o.a = *(const float4*)(q + 0); o.w = *(const float4*)(q + 4); o.b = *(const float4*)(q + 8);
;     o.k = *(const float4*)(q + 12); o.r = *(const float4*)(q + 16);
;     o.v = vb[s * 16];
;     return o;
;     ...
;       for (int s = 0; s < TB; ++s) {
;         OpsR c = n1;
;         n1 = n2;
;         if (s + 2 < TB) n2 = ld(ob, vb, s + 2);
;         f2v a01 = {c.a.x, c.a.y}, a23 = {c.a.z, c.a.w}, w01 = {c.w.x, c.w.y}, w23 = {c.w.z, c.w.w},
;             b01 = {c.b.x, c.b.y}, b23 = {c.b.z, c.b.w}, k01 = {c.k.x, c.k.y}, k23 = {c.k.z, c.k.w},
;             r01 = {c.r.x, c.r.y}, r23 = {c.r.z, c.r.w};
;         f2v vv = {c.v, c.v};
;         f2v vk01 = vv * k01, vk23 = vv * k23;
;         f2v t = S01 * a01;
;         t = S23 * a23 + t;
;         float sa = allreduce16(t.x + t.y);
;         f2v sv = {sa, sa};
;         S01 = S01 * w01 + (sv * b01 + vk01);
;         S23 = S23 * w23 + (sv * b23 + vk23);
;         f2v u = S01 * r01;
;         u = S23 * r23 + u;
;         float uu = u.x + u.y;
;         uu += dppmov<0xB1>(uu);
;         yb[s * 128] = uu;
;       }
	v_pk_mul_f32 v[186:187], v[32:33], v[160:161]
	v_pk_mul_f32 v[190:191], v[32:33], v[152:153]
	v_pk_fma_f32 v[186:187], v[34:35], v[162:163], v[186:187]
	v_pk_fma_f32 v[190:191], v[34:35], v[154:155], v[190:191]
	ds_read_b128 v[136:139], v237 offset:38400
	ds_read_b128 v[140:143], v237 offset:38416
	ds_read_b128 v[144:147], v237 offset:38432
	ds_read_b128 v[148:151], v237 offset:38448
	ds_read_b128 v[152:155], v237 offset:38464
	ds_read_b32 v156, v238 offset:1920
	v_add_f32_e32 v188, v186, v187
	v_pk_mul_f32 v[158:159], v[172:173], v[180:181] op_sel_hi:[1,0]
	v_add_f32_e32 v192, v190, v191
	v_add_f32_dpp v188, v188, v188 quad_perm:[1,0,3,2] row_mask:0xf bank_mask:0xf bound_ctrl:1
	v_pk_mul_f32 v[182:183], v[174:175], v[180:181] op_sel_hi:[1,0]
	v_add_f32_dpp v192, v192, v192 quad_perm:[1,0,3,2] row_mask:0xf bank_mask:0xf bound_ctrl:1
	v_add_f32_dpp v188, v188, v188 quad_perm:[2,3,0,1] row_mask:0xf bank_mask:0xf bound_ctrl:1
	v_pk_fma_f32 v[194:195], v[32:33], v[164:165], v[158:159]
	ds_write_b32 v193, v192 offset:13824
	v_add_f32_dpp v188, v188, v188 row_half_mirror row_mask:0xf bank_mask:0xf bound_ctrl:1
	v_pk_fma_f32 v[214:215], v[34:35], v[166:167], v[182:183]
	s_nop 0
	v_add_f32_dpp v188, v188, v188 row_mirror row_mask:0xf bank_mask:0xf bound_ctrl:1
	v_pk_fma_f32 v[32:33], v[168:169], v[188:189], v[194:195] op_sel_hi:[1,0,1]
	v_pk_fma_f32 v[34:35], v[170:171], v[188:189], v[214:215] op_sel_hi:[1,0,1]
	s_waitcnt lgkmcnt(8)
	v_pk_mul_f32 v[186:187], v[32:33], v[216:217]
	v_pk_mul_f32 v[190:191], v[32:33], v[176:177]
	v_pk_fma_f32 v[186:187], v[34:35], v[218:219], v[186:187]
	v_pk_fma_f32 v[190:191], v[34:35], v[178:179], v[190:191]
	ds_read_b128 v[160:163], v237 offset:39680
	ds_read_b128 v[164:167], v237 offset:39696
	ds_read_b128 v[168:171], v237 offset:39712
	ds_read_b128 v[172:175], v237 offset:39728
	ds_read_b128 v[176:179], v237 offset:39744
	ds_read_b32 v180, v238 offset:1984
	v_add_f32_e32 v188, v186, v187
	v_pk_mul_f32 v[158:159], v[228:229], v[184:185] op_sel_hi:[1,0]
	v_add_f32_e32 v192, v190, v191
	v_add_f32_dpp v188, v188, v188 quad_perm:[1,0,3,2] row_mask:0xf bank_mask:0xf bound_ctrl:1
	v_pk_mul_f32 v[182:183], v[230:231], v[184:185] op_sel_hi:[1,0]
	v_add_f32_dpp v192, v192, v192 quad_perm:[1,0,3,2] row_mask:0xf bank_mask:0xf bound_ctrl:1
	v_add_f32_dpp v188, v188, v188 quad_perm:[2,3,0,1] row_mask:0xf bank_mask:0xf bound_ctrl:1
	v_pk_fma_f32 v[194:195], v[32:33], v[220:221], v[158:159]
	ds_write_b32 v193, v192 offset:14336
	v_add_f32_dpp v188, v188, v188 row_half_mirror row_mask:0xf bank_mask:0xf bound_ctrl:1
	v_pk_fma_f32 v[214:215], v[34:35], v[222:223], v[182:183]
	s_nop 0
	v_add_f32_dpp v188, v188, v188 row_mirror row_mask:0xf bank_mask:0xf bound_ctrl:1
	v_pk_fma_f32 v[32:33], v[224:225], v[188:189], v[194:195] op_sel_hi:[1,0,1]
	v_pk_fma_f32 v[34:35], v[226:227], v[188:189], v[214:215] op_sel_hi:[1,0,1]
	s_waitcnt lgkmcnt(8)
	v_pk_mul_f32 v[186:187], v[32:33], v[136:137]
	v_pk_mul_f32 v[190:191], v[32:33], v[232:233]
	v_pk_fma_f32 v[186:187], v[34:35], v[138:139], v[186:187]
	v_pk_fma_f32 v[190:191], v[34:35], v[234:235], v[190:191]
	v_add_f32_e32 v188, v186, v187
	v_pk_mul_f32 v[158:159], v[148:149], v[156:157] op_sel_hi:[1,0]
	v_add_f32_e32 v192, v190, v191
	v_add_f32_dpp v188, v188, v188 quad_perm:[1,0,3,2] row_mask:0xf bank_mask:0xf bound_ctrl:1
	v_pk_mul_f32 v[182:183], v[150:151], v[156:157] op_sel_hi:[1,0]
	v_add_f32_dpp v192, v192, v192 quad_perm:[1,0,3,2] row_mask:0xf bank_mask:0xf bound_ctrl:1
	v_add_f32_dpp v188, v188, v188 quad_perm:[2,3,0,1] row_mask:0xf bank_mask:0xf bound_ctrl:1
	v_pk_fma_f32 v[194:195], v[32:33], v[140:141], v[158:159]
	ds_write_b32 v193, v192 offset:14848
	v_add_f32_dpp v188, v188, v188 row_half_mirror row_mask:0xf bank_mask:0xf bound_ctrl:1
	v_pk_fma_f32 v[214:215], v[34:35], v[142:143], v[182:183]
	s_nop 0
	v_add_f32_dpp v188, v188, v188 row_mirror row_mask:0xf bank_mask:0xf bound_ctrl:1
	v_pk_fma_f32 v[32:33], v[144:145], v[188:189], v[194:195] op_sel_hi:[1,0,1]
	v_pk_fma_f32 v[34:35], v[146:147], v[188:189], v[214:215] op_sel_hi:[1,0,1]
	s_waitcnt lgkmcnt(2)
	v_pk_mul_f32 v[186:187], v[32:33], v[160:161]
	v_pk_mul_f32 v[190:191], v[32:33], v[152:153]
	v_pk_fma_f32 v[186:187], v[34:35], v[162:163], v[186:187]
	v_pk_fma_f32 v[190:191], v[34:35], v[154:155], v[190:191]
	v_add_f32_e32 v188, v186, v187
	v_pk_mul_f32 v[158:159], v[172:173], v[180:181] op_sel_hi:[1,0]
	v_add_f32_e32 v192, v190, v191
	v_add_f32_dpp v188, v188, v188 quad_perm:[1,0,3,2] row_mask:0xf bank_mask:0xf bound_ctrl:1
	v_pk_mul_f32 v[182:183], v[174:175], v[180:181] op_sel_hi:[1,0]
	v_add_f32_dpp v192, v192, v192 quad_perm:[1,0,3,2] row_mask:0xf bank_mask:0xf bound_ctrl:1
	v_add_f32_dpp v188, v188, v188 quad_perm:[2,3,0,1] row_mask:0xf bank_mask:0xf bound_ctrl:1
	v_pk_fma_f32 v[194:195], v[32:33], v[164:165], v[158:159]
	ds_write_b32 v193, v192 offset:15360
	v_add_f32_dpp v188, v188, v188 row_half_mirror row_mask:0xf bank_mask:0xf bound_ctrl:1
	v_pk_fma_f32 v[214:215], v[34:35], v[166:167], v[182:183]
	s_nop 0
	v_add_f32_dpp v188, v188, v188 row_mirror row_mask:0xf bank_mask:0xf bound_ctrl:1
	v_pk_fma_f32 v[32:33], v[168:169], v[188:189], v[194:195] op_sel_hi:[1,0,1]
	v_pk_fma_f32 v[34:35], v[170:171], v[188:189], v[214:215] op_sel_hi:[1,0,1]
	v_pk_mul_f32 v[190:191], v[32:33], v[176:177]
	v_pk_fma_f32 v[190:191], v[34:35], v[178:179], v[190:191]
	v_add_f32_e32 v192, v190, v191
	v_add_u32_e32 v41, 1, v38
	s_nop 0
	v_add_f32_dpp v192, v192, v192 quad_perm:[1,0,3,2] row_mask:0xf bank_mask:0xf bound_ctrl:1
	ds_write_b32 v193, v192 offset:15872
